# speedup vs baseline: 1.0557x; 1.0291x over previous
; template <int MASK>
; __global__ void __launch_bounds__(256, 2) fwd_megakernel_t(Params p) {
;     ...
;         __syncthreads();
;         {
;           const int row = tid >> 1, hf = tid & 1;
;           float ss = 0.f;
; #pragma unroll
;           for (int q = 0; q < 16; q++) ss += rowsq[(size_t)(hf * 16 + q) * T_ + m0 + row];
;           const float o = __shfl_xor(ss, 1);
;           ss = hf ? (o + ss) : (ss + o);
;           if (hf == 0) {
;             const float rv_ = rsqrtf(ss * (1.f / 2048.f) + EPS_);
;             s_rinv[row] = rv_;
;             if (nt == 0) rinvx[m0 + row] = rv_;
;           }
;         }
.LBB0_275:
	s_lshl_b32 s6, s15, 7
	s_ashr_i32 s7, s6, 31
	v_lshl_add_u64 v[0:1], s[6:7], 2, v[140:141]
	s_barrier
	global_load_dword v8, v[0:1], off
	v_add_co_u32_e32 v24, vcc, 0x10000, v0
	s_nop 1
	v_addc_co_u32_e32 v25, vcc, 0, v1, vcc
	global_load_dword v9, v[24:25], off
	v_add_co_u32_e32 v24, vcc, 0x20000, v0
	s_nop 1
	v_addc_co_u32_e32 v25, vcc, 0, v1, vcc
	global_load_dword v10, v[24:25], off
	v_add_co_u32_e32 v24, vcc, 0x30000, v0
	s_nop 1
	v_addc_co_u32_e32 v25, vcc, 0, v1, vcc
	global_load_dword v11, v[24:25], off
	v_add_co_u32_e32 v24, vcc, 0x40000, v0
	s_nop 1
	v_addc_co_u32_e32 v25, vcc, 0, v1, vcc
	global_load_dword v12, v[24:25], off
	v_add_co_u32_e32 v24, vcc, 0x50000, v0
	s_nop 1
	v_addc_co_u32_e32 v25, vcc, 0, v1, vcc
	global_load_dword v13, v[24:25], off
	v_add_co_u32_e32 v24, vcc, 0x60000, v0
	s_nop 1
	v_addc_co_u32_e32 v25, vcc, 0, v1, vcc
	global_load_dword v14, v[24:25], off
	v_add_co_u32_e32 v24, vcc, 0x70000, v0
	s_nop 1
	v_addc_co_u32_e32 v25, vcc, 0, v1, vcc
	global_load_dword v15, v[24:25], off
	v_add_co_u32_e32 v24, vcc, 0x80000, v0
	s_nop 1
	v_addc_co_u32_e32 v25, vcc, 0, v1, vcc
	global_load_dword v16, v[24:25], off
	v_add_co_u32_e32 v24, vcc, 0x90000, v0
	s_nop 1
	v_addc_co_u32_e32 v25, vcc, 0, v1, vcc
	global_load_dword v17, v[24:25], off
	v_add_co_u32_e32 v24, vcc, 0xa0000, v0
	s_nop 1
	v_addc_co_u32_e32 v25, vcc, 0, v1, vcc
	global_load_dword v18, v[24:25], off
	v_add_co_u32_e32 v24, vcc, 0xb0000, v0
	s_nop 1
	v_addc_co_u32_e32 v25, vcc, 0, v1, vcc
	global_load_dword v19, v[24:25], off
	v_add_co_u32_e32 v24, vcc, 0xc0000, v0
	s_nop 1
	v_addc_co_u32_e32 v25, vcc, 0, v1, vcc
	global_load_dword v20, v[24:25], off
	v_add_co_u32_e32 v24, vcc, 0xd0000, v0
	s_nop 1
	v_addc_co_u32_e32 v25, vcc, 0, v1, vcc
	global_load_dword v21, v[24:25], off
	v_add_co_u32_e32 v24, vcc, 0xe0000, v0
	s_nop 1
	v_addc_co_u32_e32 v25, vcc, 0, v1, vcc
	global_load_dword v22, v[24:25], off
	v_add_co_u32_e32 v24, vcc, 0xf0000, v0
	s_nop 1
	v_addc_co_u32_e32 v25, vcc, 0, v1, vcc
	global_load_dword v23, v[24:25], off
	v_cmp_lt_i32_e32 vcc, v194, v189
	s_nop 1
	v_cndmask_b32_e32 v1, v187, v194, vcc
	v_lshlrev_b32_e32 v1, 2, v1
	s_waitcnt vmcnt(0)
	v_add_f32_e32 v4, 0, v8
	v_add_f32_e32 v4, v4, v9
	v_add_f32_e32 v4, v4, v10
	v_add_f32_e32 v4, v4, v11
	v_add_f32_e32 v4, v4, v12
	v_add_f32_e32 v4, v4, v13
	v_add_f32_e32 v4, v4, v14
	v_add_f32_e32 v4, v4, v15
	v_add_f32_e32 v4, v4, v16
	v_add_f32_e32 v4, v4, v17
	v_add_f32_e32 v4, v4, v18
	v_add_f32_e32 v4, v4, v19
	v_add_f32_e32 v4, v4, v20
	v_add_f32_e32 v4, v4, v21
	v_add_f32_e32 v4, v4, v22
	v_add_f32_e32 v0, v4, v23
	ds_bpermute_b32 v1, v1, v0
	s_and_saveexec_b64 s[8:9], s[4:5]
	s_cbranch_execz .LBB0_278
	s_waitcnt lgkmcnt(0)
	v_add_f32_e32 v0, v0, v1
	v_fmamk_f32 v0, v0, 0x3a000000, v155
	v_mul_f32_e32 v1, 0x4b800000, v0
	v_cmp_gt_f32_e32 vcc, s62, v0
	s_cmp_lg_u32 s14, 0
	s_nop 0
	v_cndmask_b32_e32 v0, v0, v1, vcc
	v_rsq_f32_e32 v0, v0
	s_nop 0
	v_mul_f32_e32 v1, 0x45800000, v0
	v_cndmask_b32_e32 v0, v0, v1, vcc
	ds_write_b32 v129, v0
	s_cbranch_scc1 .LBB0_278
	v_add_u32_e32 v2, s6, v128
	v_ashrrev_i32_e32 v3, 31, v2
	v_lshl_add_u64 v[2:3], v[2:3], 2, s[80:81]
	global_store_dword v[2:3], v0, off

; DI float bf2f(u16 v) { return __uint_as_float(((unsigned)v) << 16); }
; DI int crow(int reg, int h) { return (reg & 3) + 8 * (reg >> 2) + 4 * h; }
; template <int MASK>
; __global__ void __launch_bounds__(256, 2) fwd_megakernel_t(Params p) {
;     ...
; #pragma unroll
;         for (int i = 0; i < 2; i++) {
;           float sq[16];
; #pragma unroll
;           for (int r = 0; r < 16; r++) sq[r] = 0.f;
; #pragma unroll
;           for (int j = 0; j < 2; j++)
; #pragma unroll
;             for (int r = 0; r < 16; r++) {
;               const int m = m0 + wm * 64 + i * 32 + crow(r, hh), n = n0 + wn * 64 + j * 32 + cc;
;               const float v = bf2f(xb[(size_t)m * 2048 + n]) + acc[i][j][r];
;               xb[(size_t)m * 2048 + n] = f2bf(v);
;               sq[r] += v * v;
;             }
.LBB0_308:
	v_add_u32_e32 v66, s6, v137
	v_or_b32_e32 v68, s8, v153
	v_ashrrev_i32_e32 v67, 31, v66
	v_ashrrev_i32_e32 v69, 31, v68
	v_lshlrev_b64 v[70:71], 12, v[66:67]
	v_lshl_add_u64 v[68:69], v[68:69], 1, s[82:83]
	v_lshl_add_u64 v[82:83], v[68:69], 0, v[70:71]
	v_lshl_or_b32 v64, s17, 1, v139
	v_ashrrev_i32_e32 v65, 31, v64
	v_lshlrev_b64 v[64:65], 16, v[64:65]
	s_ashr_i32 s7, s6, 31
	v_lshl_add_u64 v[64:65], s[46:47], 0, v[64:65]
	v_lshl_add_u64 v[64:65], s[6:7], 2, v[64:65]
	v_lshl_add_u64 v[64:65], v[134:135], 2, v[64:65]
	v_lshlrev_b32_e32 v144, 2, v138
	v_mov_b32_e32 v145, v151
	v_lshl_add_u64 v[146:147], v[64:65], 0, v[144:145]
	v_readfirstlane_b32 s30, v82
	v_readfirstlane_b32 s31, v83
	s_nop 1
	v_subrev_u32_e32 v144, s30, v82
	s_waitcnt vmcnt(0)
	s_nop 3
	s_add_u32 s22, s30, 0x0
	s_addc_u32 s23, s31, 0
	global_load_ushort v64, v144, s[22:23]
	global_load_ushort v80, v144, s[22:23] offset:64
	s_add_u32 s22, s30, 0x1000
	s_addc_u32 s23, s31, 0
	global_load_ushort v65, v144, s[22:23]
	global_load_ushort v81, v144, s[22:23] offset:64
	s_add_u32 s22, s30, 0x2000
	s_addc_u32 s23, s31, 0
	global_load_ushort v66, v144, s[22:23]
	global_load_ushort v82, v144, s[22:23] offset:64
	s_add_u32 s22, s30, 0x3000
	s_addc_u32 s23, s31, 0
	global_load_ushort v67, v144, s[22:23]
	global_load_ushort v83, v144, s[22:23] offset:64
	s_add_u32 s22, s30, 0x8000
	s_addc_u32 s23, s31, 0
	global_load_ushort v68, v144, s[22:23]
	global_load_ushort v84, v144, s[22:23] offset:64
	s_add_u32 s22, s30, 0x9000
	s_addc_u32 s23, s31, 0
	global_load_ushort v69, v144, s[22:23]
	global_load_ushort v85, v144, s[22:23] offset:64
	s_add_u32 s22, s30, 0xa000
	s_addc_u32 s23, s31, 0
	global_load_ushort v70, v144, s[22:23]
	global_load_ushort v86, v144, s[22:23] offset:64
	s_add_u32 s22, s30, 0xb000
	s_addc_u32 s23, s31, 0
	global_load_ushort v71, v144, s[22:23]
	global_load_ushort v87, v144, s[22:23] offset:64
	s_add_u32 s22, s30, 0x10000
	s_addc_u32 s23, s31, 0
	global_load_ushort v72, v144, s[22:23]
	global_load_ushort v88, v144, s[22:23] offset:64
	s_add_u32 s22, s30, 0x11000
	s_addc_u32 s23, s31, 0
	global_load_ushort v73, v144, s[22:23]
	global_load_ushort v89, v144, s[22:23] offset:64
	s_add_u32 s22, s30, 0x12000
	s_addc_u32 s23, s31, 0
	global_load_ushort v74, v144, s[22:23]
	global_load_ushort v90, v144, s[22:23] offset:64
	s_add_u32 s22, s30, 0x13000
	s_addc_u32 s23, s31, 0
	global_load_ushort v75, v144, s[22:23]
	global_load_ushort v91, v144, s[22:23] offset:64
	s_add_u32 s22, s30, 0x18000
	s_addc_u32 s23, s31, 0
	global_load_ushort v76, v144, s[22:23]
	global_load_ushort v92, v144, s[22:23] offset:64
	s_add_u32 s22, s30, 0x19000
	s_addc_u32 s23, s31, 0
	global_load_ushort v77, v144, s[22:23]
	global_load_ushort v93, v144, s[22:23] offset:64
	s_add_u32 s22, s30, 0x1a000
	s_addc_u32 s23, s31, 0
	global_load_ushort v78, v144, s[22:23]
	global_load_ushort v94, v144, s[22:23] offset:64
	s_add_u32 s22, s30, 0x1b000
	s_addc_u32 s23, s31, 0
	global_load_ushort v79, v144, s[22:23]
	global_load_ushort v95, v144, s[22:23] offset:64
	s_waitcnt vmcnt(0)
	v_lshlrev_b32_e32 v64, 16, v64
	v_add_f32_e32 v48, v48, v64
	v_cvt_pk_bf16_f32 v64, v48, v48
	v_lshlrev_b32_e32 v65, 16, v65
	v_add_f32_e32 v49, v49, v65
	v_cvt_pk_bf16_f32 v65, v49, v49
	v_lshlrev_b32_e32 v66, 16, v66
	v_add_f32_e32 v50, v50, v66
	v_cvt_pk_bf16_f32 v66, v50, v50
	v_lshlrev_b32_e32 v67, 16, v67
	v_add_f32_e32 v51, v51, v67
	v_cvt_pk_bf16_f32 v67, v51, v51
	v_lshlrev_b32_e32 v68, 16, v68
	v_add_f32_e32 v52, v52, v68
	v_cvt_pk_bf16_f32 v68, v52, v52
	v_lshlrev_b32_e32 v69, 16, v69
	v_add_f32_e32 v53, v53, v69
	v_cvt_pk_bf16_f32 v69, v53, v53
	v_lshlrev_b32_e32 v70, 16, v70
	v_add_f32_e32 v54, v54, v70
	v_cvt_pk_bf16_f32 v70, v54, v54
	v_lshlrev_b32_e32 v71, 16, v71
	v_add_f32_e32 v55, v55, v71
	v_cvt_pk_bf16_f32 v71, v55, v55
	v_lshlrev_b32_e32 v72, 16, v72
	v_add_f32_e32 v56, v56, v72
	v_cvt_pk_bf16_f32 v72, v56, v56
	v_lshlrev_b32_e32 v73, 16, v73
	v_add_f32_e32 v57, v57, v73
	v_cvt_pk_bf16_f32 v73, v57, v57
	v_lshlrev_b32_e32 v74, 16, v74
	v_add_f32_e32 v58, v58, v74
	v_cvt_pk_bf16_f32 v74, v58, v58
	v_lshlrev_b32_e32 v75, 16, v75
	v_add_f32_e32 v59, v59, v75
	v_cvt_pk_bf16_f32 v75, v59, v59
	v_lshlrev_b32_e32 v76, 16, v76
	v_add_f32_e32 v60, v60, v76
	v_cvt_pk_bf16_f32 v76, v60, v60
	v_lshlrev_b32_e32 v77, 16, v77
	v_add_f32_e32 v61, v61, v77
	v_cvt_pk_bf16_f32 v77, v61, v61
	v_lshlrev_b32_e32 v78, 16, v78
	v_add_f32_e32 v62, v62, v78
	v_cvt_pk_bf16_f32 v78, v62, v62
	v_lshlrev_b32_e32 v79, 16, v79
	v_add_f32_e32 v63, v63, v79
	v_cvt_pk_bf16_f32 v79, v63, v63
	v_lshlrev_b32_e32 v80, 16, v80
	v_add_f32_e32 v32, v32, v80
	v_cvt_pk_bf16_f32 v80, v32, v32
	v_lshlrev_b32_e32 v81, 16, v81
	v_add_f32_e32 v33, v33, v81
	v_cvt_pk_bf16_f32 v81, v33, v33
	v_lshlrev_b32_e32 v82, 16, v82
	v_add_f32_e32 v34, v34, v82
	v_cvt_pk_bf16_f32 v82, v34, v34
	v_lshlrev_b32_e32 v83, 16, v83
	v_add_f32_e32 v35, v35, v83
	v_cvt_pk_bf16_f32 v83, v35, v35
	v_lshlrev_b32_e32 v84, 16, v84
	v_add_f32_e32 v36, v36, v84
	v_cvt_pk_bf16_f32 v84, v36, v36
	v_lshlrev_b32_e32 v85, 16, v85
	v_add_f32_e32 v37, v37, v85
	v_cvt_pk_bf16_f32 v85, v37, v37
	v_lshlrev_b32_e32 v86, 16, v86
	v_add_f32_e32 v38, v38, v86
	v_cvt_pk_bf16_f32 v86, v38, v38
	v_lshlrev_b32_e32 v87, 16, v87
	v_add_f32_e32 v39, v39, v87
	v_cvt_pk_bf16_f32 v87, v39, v39
	v_lshlrev_b32_e32 v88, 16, v88
	v_add_f32_e32 v40, v40, v88
	v_cvt_pk_bf16_f32 v88, v40, v40
	v_lshlrev_b32_e32 v89, 16, v89
	v_add_f32_e32 v41, v41, v89
	v_cvt_pk_bf16_f32 v89, v41, v41
	v_lshlrev_b32_e32 v90, 16, v90
	v_add_f32_e32 v42, v42, v90
	v_cvt_pk_bf16_f32 v90, v42, v42
	v_lshlrev_b32_e32 v91, 16, v91
; DI float bf2f(u16 v) { return __uint_as_float(((unsigned)v) << 16); }
; DI int crow(int reg, int h) { return (reg & 3) + 8 * (reg >> 2) + 4 * h; }
; template <int MASK>
; __global__ void __launch_bounds__(256, 2) fwd_megakernel_t(Params p) {
;     ...
;           for (int j = 0; j < 2; j++)
; #pragma unroll
;             for (int r = 0; r < 16; r++) {
;               const int m = m0 + wm * 64 + i * 32 + crow(r, hh), n = n0 + wn * 64 + j * 32 + cc;
;               const float v = bf2f(xb[(size_t)m * 2048 + n]) + acc[i][j][r];
;               xb[(size_t)m * 2048 + n] = f2bf(v);
;               sq[r] += v * v;
;             }
	v_add_f32_e32 v43, v43, v91
	v_cvt_pk_bf16_f32 v91, v43, v43
	v_lshlrev_b32_e32 v92, 16, v92
	v_add_f32_e32 v44, v44, v92
	v_cvt_pk_bf16_f32 v92, v44, v44
	v_lshlrev_b32_e32 v93, 16, v93
	v_add_f32_e32 v45, v45, v93
	v_cvt_pk_bf16_f32 v93, v45, v45
	v_lshlrev_b32_e32 v94, 16, v94
	v_add_f32_e32 v46, v46, v94
	v_cvt_pk_bf16_f32 v94, v46, v46
	v_lshlrev_b32_e32 v95, 16, v95
	v_add_f32_e32 v47, v47, v95
	v_cvt_pk_bf16_f32 v95, v47, v47
	s_add_u32 s22, s30, 0x20000
	s_addc_u32 s23, s31, 0
	global_load_ushort v96, v144, s[22:23]
	global_load_ushort v112, v144, s[22:23] offset:64
	s_add_u32 s22, s30, 0x21000
	s_addc_u32 s23, s31, 0
	global_load_ushort v97, v144, s[22:23]
	global_load_ushort v113, v144, s[22:23] offset:64
	s_add_u32 s22, s30, 0x22000
	s_addc_u32 s23, s31, 0
	global_load_ushort v98, v144, s[22:23]
	global_load_ushort v114, v144, s[22:23] offset:64
	s_add_u32 s22, s30, 0x23000
	s_addc_u32 s23, s31, 0
	global_load_ushort v99, v144, s[22:23]
	global_load_ushort v115, v144, s[22:23] offset:64
	s_add_u32 s22, s30, 0x28000
	s_addc_u32 s23, s31, 0
	global_load_ushort v100, v144, s[22:23]
	global_load_ushort v116, v144, s[22:23] offset:64
	s_add_u32 s22, s30, 0x29000
	s_addc_u32 s23, s31, 0
	global_load_ushort v101, v144, s[22:23]
	global_load_ushort v117, v144, s[22:23] offset:64
	s_add_u32 s22, s30, 0x2a000
	s_addc_u32 s23, s31, 0
	global_load_ushort v102, v144, s[22:23]
	global_load_ushort v118, v144, s[22:23] offset:64
	s_add_u32 s22, s30, 0x2b000
	s_addc_u32 s23, s31, 0
	global_load_ushort v103, v144, s[22:23]
	global_load_ushort v119, v144, s[22:23] offset:64
	s_add_u32 s22, s30, 0x30000
	s_addc_u32 s23, s31, 0
	global_load_ushort v104, v144, s[22:23]
	global_load_ushort v120, v144, s[22:23] offset:64
	s_add_u32 s22, s30, 0x31000
	s_addc_u32 s23, s31, 0
	global_load_ushort v105, v144, s[22:23]
	global_load_ushort v121, v144, s[22:23] offset:64
	s_add_u32 s22, s30, 0x32000
	s_addc_u32 s23, s31, 0
	global_load_ushort v106, v144, s[22:23]
	global_load_ushort v122, v144, s[22:23] offset:64
	s_add_u32 s22, s30, 0x33000
	s_addc_u32 s23, s31, 0
	global_load_ushort v107, v144, s[22:23]
	global_load_ushort v123, v144, s[22:23] offset:64
	s_add_u32 s22, s30, 0x38000
	s_addc_u32 s23, s31, 0
	global_load_ushort v108, v144, s[22:23]
	global_load_ushort v124, v144, s[22:23] offset:64
	s_add_u32 s22, s30, 0x39000
	s_addc_u32 s23, s31, 0
	global_load_ushort v109, v144, s[22:23]
	global_load_ushort v125, v144, s[22:23] offset:64
	s_add_u32 s22, s30, 0x3a000
	s_addc_u32 s23, s31, 0
	global_load_ushort v110, v144, s[22:23]
	global_load_ushort v126, v144, s[22:23] offset:64
	s_add_u32 s22, s30, 0x3b000
	s_addc_u32 s23, s31, 0
	global_load_ushort v111, v144, s[22:23]
	global_load_ushort v127, v144, s[22:23] offset:64
	s_add_u32 s22, s30, 0x0
	s_addc_u32 s23, s31, 0
	global_store_short v144, v64, s[22:23]
	s_add_u32 s22, s30, 0x1000
	s_addc_u32 s23, s31, 0
	global_store_short v144, v65, s[22:23]
	s_add_u32 s22, s30, 0x2000
	s_addc_u32 s23, s31, 0
	global_store_short v144, v66, s[22:23]
	s_add_u32 s22, s30, 0x3000
	s_addc_u32 s23, s31, 0
	global_store_short v144, v67, s[22:23]
	s_add_u32 s22, s30, 0x8000
	s_addc_u32 s23, s31, 0
	global_store_short v144, v68, s[22:23]
	s_add_u32 s22, s30, 0x9000
	s_addc_u32 s23, s31, 0
	global_store_short v144, v69, s[22:23]
	s_add_u32 s22, s30, 0xa000
	s_addc_u32 s23, s31, 0
	global_store_short v144, v70, s[22:23]
	s_add_u32 s22, s30, 0xb000
	s_addc_u32 s23, s31, 0
	global_store_short v144, v71, s[22:23]
	s_add_u32 s22, s30, 0x10000
	s_addc_u32 s23, s31, 0
	global_store_short v144, v72, s[22:23]
	s_add_u32 s22, s30, 0x11000
	s_addc_u32 s23, s31, 0
	global_store_short v144, v73, s[22:23]
	s_add_u32 s22, s30, 0x12000
	s_addc_u32 s23, s31, 0
	global_store_short v144, v74, s[22:23]
	s_add_u32 s22, s30, 0x13000
	s_addc_u32 s23, s31, 0
	global_store_short v144, v75, s[22:23]
	s_add_u32 s22, s30, 0x18000
	s_addc_u32 s23, s31, 0
	global_store_short v144, v76, s[22:23]
	s_add_u32 s22, s30, 0x19000
	s_addc_u32 s23, s31, 0
	global_store_short v144, v77, s[22:23]
	s_add_u32 s22, s30, 0x1a000
	s_addc_u32 s23, s31, 0
	global_store_short v144, v78, s[22:23]
	s_add_u32 s22, s30, 0x1b000
	s_addc_u32 s23, s31, 0
	global_store_short v144, v79, s[22:23]
	s_waitcnt vmcnt(16)
; DI float bf2f(u16 v) { return __uint_as_float(((unsigned)v) << 16); }
; DI int crow(int reg, int h) { return (reg & 3) + 8 * (reg >> 2) + 4 * h; }
; template <int MASK>
; __global__ void __launch_bounds__(256, 2) fwd_megakernel_t(Params p) {
;     ...
;           for (int j = 0; j < 2; j++)
; #pragma unroll
;             for (int r = 0; r < 16; r++) {
;               const int m = m0 + wm * 64 + i * 32 + crow(r, hh), n = n0 + wn * 64 + j * 32 + cc;
;               const float v = bf2f(xb[(size_t)m * 2048 + n]) + acc[i][j][r];
;               xb[(size_t)m * 2048 + n] = f2bf(v);
;               sq[r] += v * v;
;             }
	v_lshlrev_b32_e32 v96, 16, v96
	v_add_f32_e32 v16, v16, v96
	v_cvt_pk_bf16_f32 v96, v16, v16
	v_lshlrev_b32_e32 v97, 16, v97
	v_add_f32_e32 v17, v17, v97
	v_cvt_pk_bf16_f32 v97, v17, v17
	v_lshlrev_b32_e32 v98, 16, v98
	v_add_f32_e32 v18, v18, v98
	v_cvt_pk_bf16_f32 v98, v18, v18
	v_lshlrev_b32_e32 v99, 16, v99
	v_add_f32_e32 v19, v19, v99
	v_cvt_pk_bf16_f32 v99, v19, v19
	v_lshlrev_b32_e32 v100, 16, v100
	v_add_f32_e32 v20, v20, v100
	v_cvt_pk_bf16_f32 v100, v20, v20
	v_lshlrev_b32_e32 v101, 16, v101
	v_add_f32_e32 v21, v21, v101
	v_cvt_pk_bf16_f32 v101, v21, v21
	v_lshlrev_b32_e32 v102, 16, v102
	v_add_f32_e32 v22, v22, v102
	v_cvt_pk_bf16_f32 v102, v22, v22
	v_lshlrev_b32_e32 v103, 16, v103
	v_add_f32_e32 v23, v23, v103
	v_cvt_pk_bf16_f32 v103, v23, v23
	v_lshlrev_b32_e32 v104, 16, v104
	v_add_f32_e32 v24, v24, v104
	v_cvt_pk_bf16_f32 v104, v24, v24
	v_lshlrev_b32_e32 v105, 16, v105
	v_add_f32_e32 v25, v25, v105
	v_cvt_pk_bf16_f32 v105, v25, v25
	v_lshlrev_b32_e32 v106, 16, v106
	v_add_f32_e32 v26, v26, v106
	v_cvt_pk_bf16_f32 v106, v26, v26
	v_lshlrev_b32_e32 v107, 16, v107
	v_add_f32_e32 v27, v27, v107
	v_cvt_pk_bf16_f32 v107, v27, v27
	v_lshlrev_b32_e32 v108, 16, v108
	v_add_f32_e32 v28, v28, v108
	v_cvt_pk_bf16_f32 v108, v28, v28
	v_lshlrev_b32_e32 v109, 16, v109
	v_add_f32_e32 v29, v29, v109
	v_cvt_pk_bf16_f32 v109, v29, v29
	v_lshlrev_b32_e32 v110, 16, v110
	v_add_f32_e32 v30, v30, v110
	v_cvt_pk_bf16_f32 v110, v30, v30
	v_lshlrev_b32_e32 v111, 16, v111
	v_add_f32_e32 v31, v31, v111
	v_cvt_pk_bf16_f32 v111, v31, v31
	v_lshlrev_b32_e32 v112, 16, v112
	v_add_f32_e32 v0, v0, v112
	v_cvt_pk_bf16_f32 v112, v0, v0
	v_lshlrev_b32_e32 v113, 16, v113
	v_add_f32_e32 v1, v1, v113
	v_cvt_pk_bf16_f32 v113, v1, v1
	v_lshlrev_b32_e32 v114, 16, v114
	v_add_f32_e32 v2, v2, v114
	v_cvt_pk_bf16_f32 v114, v2, v2
	v_lshlrev_b32_e32 v115, 16, v115
	v_add_f32_e32 v3, v3, v115
	v_cvt_pk_bf16_f32 v115, v3, v3
	v_lshlrev_b32_e32 v116, 16, v116
	v_add_f32_e32 v4, v4, v116
	v_cvt_pk_bf16_f32 v116, v4, v4
	v_lshlrev_b32_e32 v117, 16, v117
	v_add_f32_e32 v5, v5, v117
	v_cvt_pk_bf16_f32 v117, v5, v5
	v_lshlrev_b32_e32 v118, 16, v118
	v_add_f32_e32 v6, v6, v118
	v_cvt_pk_bf16_f32 v118, v6, v6
	v_lshlrev_b32_e32 v119, 16, v119
	v_add_f32_e32 v7, v7, v119
	v_cvt_pk_bf16_f32 v119, v7, v7
	v_lshlrev_b32_e32 v120, 16, v120
	v_add_f32_e32 v8, v8, v120
	v_cvt_pk_bf16_f32 v120, v8, v8
	v_lshlrev_b32_e32 v121, 16, v121
	v_add_f32_e32 v9, v9, v121
	v_cvt_pk_bf16_f32 v121, v9, v9
	v_lshlrev_b32_e32 v122, 16, v122
	v_add_f32_e32 v10, v10, v122
	v_cvt_pk_bf16_f32 v122, v10, v10
	v_lshlrev_b32_e32 v123, 16, v123
	v_add_f32_e32 v11, v11, v123
	v_cvt_pk_bf16_f32 v123, v11, v11
	v_lshlrev_b32_e32 v124, 16, v124
	v_add_f32_e32 v12, v12, v124
	v_cvt_pk_bf16_f32 v124, v12, v12
	v_lshlrev_b32_e32 v125, 16, v125
	v_add_f32_e32 v13, v13, v125
	v_cvt_pk_bf16_f32 v125, v13, v13
	v_lshlrev_b32_e32 v126, 16, v126
	v_add_f32_e32 v14, v14, v126
	v_cvt_pk_bf16_f32 v126, v14, v14
	v_lshlrev_b32_e32 v127, 16, v127
	v_add_f32_e32 v15, v15, v127
	v_cvt_pk_bf16_f32 v127, v15, v15
	s_add_u32 s22, s30, 0x0
	s_addc_u32 s23, s31, 0
	global_store_short v144, v80, s[22:23] offset:64
	s_add_u32 s22, s30, 0x1000
	s_addc_u32 s23, s31, 0
	global_store_short v144, v81, s[22:23] offset:64
	s_add_u32 s22, s30, 0x2000
	s_addc_u32 s23, s31, 0
	global_store_short v144, v82, s[22:23] offset:64
	s_add_u32 s22, s30, 0x3000
	s_addc_u32 s23, s31, 0
	global_store_short v144, v83, s[22:23] offset:64
	s_add_u32 s22, s30, 0x8000
	s_addc_u32 s23, s31, 0
	global_store_short v144, v84, s[22:23] offset:64
	s_add_u32 s22, s30, 0x9000
	s_addc_u32 s23, s31, 0
	global_store_short v144, v85, s[22:23] offset:64
	s_add_u32 s22, s30, 0xa000
	s_addc_u32 s23, s31, 0
	global_store_short v144, v86, s[22:23] offset:64
	s_add_u32 s22, s30, 0xb000
	s_addc_u32 s23, s31, 0
	global_store_short v144, v87, s[22:23] offset:64
	s_add_u32 s22, s30, 0x10000
	s_addc_u32 s23, s31, 0
	global_store_short v144, v88, s[22:23] offset:64
	s_add_u32 s22, s30, 0x11000
	s_addc_u32 s23, s31, 0
	global_store_short v144, v89, s[22:23] offset:64
	s_add_u32 s22, s30, 0x12000
	s_addc_u32 s23, s31, 0
	global_store_short v144, v90, s[22:23] offset:64
	s_add_u32 s22, s30, 0x13000
	s_addc_u32 s23, s31, 0
	global_store_short v144, v91, s[22:23] offset:64
	s_add_u32 s22, s30, 0x18000
	s_addc_u32 s23, s31, 0
	global_store_short v144, v92, s[22:23] offset:64
	s_add_u32 s22, s30, 0x19000
	s_addc_u32 s23, s31, 0
	global_store_short v144, v93, s[22:23] offset:64
	s_add_u32 s22, s30, 0x1a000
	s_addc_u32 s23, s31, 0
	global_store_short v144, v94, s[22:23] offset:64
	s_add_u32 s22, s30, 0x1b000
	s_addc_u32 s23, s31, 0
	global_store_short v144, v95, s[22:23] offset:64
	s_add_u32 s22, s30, 0x20000
	s_addc_u32 s23, s31, 0
	global_store_short v144, v96, s[22:23]
	s_add_u32 s22, s30, 0x21000
	s_addc_u32 s23, s31, 0
	global_store_short v144, v97, s[22:23]
	s_add_u32 s22, s30, 0x22000
	s_addc_u32 s23, s31, 0
	global_store_short v144, v98, s[22:23]
	s_add_u32 s22, s30, 0x23000
	s_addc_u32 s23, s31, 0
	global_store_short v144, v99, s[22:23]
	s_add_u32 s22, s30, 0x28000
	s_addc_u32 s23, s31, 0
	global_store_short v144, v100, s[22:23]
	s_add_u32 s22, s30, 0x29000
	s_addc_u32 s23, s31, 0
	global_store_short v144, v101, s[22:23]
	s_add_u32 s22, s30, 0x2a000
	s_addc_u32 s23, s31, 0
	global_store_short v144, v102, s[22:23]
	s_add_u32 s22, s30, 0x2b000
	s_addc_u32 s23, s31, 0
	global_store_short v144, v103, s[22:23]
	s_add_u32 s22, s30, 0x30000
	s_addc_u32 s23, s31, 0
	global_store_short v144, v104, s[22:23]
	s_add_u32 s22, s30, 0x31000
	s_addc_u32 s23, s31, 0
	global_store_short v144, v105, s[22:23]
	s_add_u32 s22, s30, 0x32000
	s_addc_u32 s23, s31, 0
	global_store_short v144, v106, s[22:23]
	s_add_u32 s22, s30, 0x33000
	s_addc_u32 s23, s31, 0
	global_store_short v144, v107, s[22:23]
	s_add_u32 s22, s30, 0x38000
	s_addc_u32 s23, s31, 0
	global_store_short v144, v108, s[22:23]
	s_add_u32 s22, s30, 0x39000
	s_addc_u32 s23, s31, 0
	global_store_short v144, v109, s[22:23]
	s_add_u32 s22, s30, 0x3a000
	s_addc_u32 s23, s31, 0
	global_store_short v144, v110, s[22:23]
	s_add_u32 s22, s30, 0x3b000
	s_addc_u32 s23, s31, 0
	global_store_short v144, v111, s[22:23]
	s_waitcnt vmcnt(32)
; DI float bf2f(u16 v) { return __uint_as_float(((unsigned)v) << 16); }
; DI int crow(int reg, int h) { return (reg & 3) + 8 * (reg >> 2) + 4 * h; }
; template <int MASK>
; __global__ void __launch_bounds__(256, 2) fwd_megakernel_t(Params p) {
;     ...
;           for (int j = 0; j < 2; j++)
; #pragma unroll
;             for (int r = 0; r < 16; r++) {
;               const int m = m0 + wm * 64 + i * 32 + crow(r, hh), n = n0 + wn * 64 + j * 32 + cc;
;               const float v = bf2f(xb[(size_t)m * 2048 + n]) + acc[i][j][r];
;               xb[(size_t)m * 2048 + n] = f2bf(v);
;               sq[r] += v * v;
;             }
; #pragma unroll
;           for (int r = 0; r < 16; r++) {
;             float v = sq[r];
; #pragma unroll
;             for (int msk = 16; msk >= 1; msk >>= 1) v += __shfl_xor(v, msk);
;             if (cc == 0) rowsq[(size_t)(nt * 2 + wn) * T_ + m0 + wm * 64 + i * 32 + crow(r, hh)] = v;
;           }
	s_add_u32 s22, s30, 0x20000
	s_addc_u32 s23, s31, 0
	global_store_short v144, v112, s[22:23] offset:64
	s_add_u32 s22, s30, 0x21000
	s_addc_u32 s23, s31, 0
	global_store_short v144, v113, s[22:23] offset:64
	s_add_u32 s22, s30, 0x22000
	s_addc_u32 s23, s31, 0
	global_store_short v144, v114, s[22:23] offset:64
	s_add_u32 s22, s30, 0x23000
	s_addc_u32 s23, s31, 0
	global_store_short v144, v115, s[22:23] offset:64
	s_add_u32 s22, s30, 0x28000
	s_addc_u32 s23, s31, 0
	global_store_short v144, v116, s[22:23] offset:64
	s_add_u32 s22, s30, 0x29000
	s_addc_u32 s23, s31, 0
	global_store_short v144, v117, s[22:23] offset:64
	s_add_u32 s22, s30, 0x2a000
	s_addc_u32 s23, s31, 0
	global_store_short v144, v118, s[22:23] offset:64
	s_add_u32 s22, s30, 0x2b000
	s_addc_u32 s23, s31, 0
	global_store_short v144, v119, s[22:23] offset:64
	s_add_u32 s22, s30, 0x30000
	s_addc_u32 s23, s31, 0
	global_store_short v144, v120, s[22:23] offset:64
	s_add_u32 s22, s30, 0x31000
	s_addc_u32 s23, s31, 0
	global_store_short v144, v121, s[22:23] offset:64
	s_add_u32 s22, s30, 0x32000
	s_addc_u32 s23, s31, 0
	global_store_short v144, v122, s[22:23] offset:64
	s_add_u32 s22, s30, 0x33000
	s_addc_u32 s23, s31, 0
	global_store_short v144, v123, s[22:23] offset:64
	s_add_u32 s22, s30, 0x38000
	s_addc_u32 s23, s31, 0
	global_store_short v144, v124, s[22:23] offset:64
	s_add_u32 s22, s30, 0x39000
	s_addc_u32 s23, s31, 0
	global_store_short v144, v125, s[22:23] offset:64
	s_add_u32 s22, s30, 0x3a000
	s_addc_u32 s23, s31, 0
	global_store_short v144, v126, s[22:23] offset:64
	s_add_u32 s22, s30, 0x3b000
	s_addc_u32 s23, s31, 0
	global_store_short v144, v127, s[22:23] offset:64
	v_mul_f32_e32 v32, v32, v32
	v_fmac_f32_e32 v32, v48, v48
	v_mov_b32_e32 v48, v32
	s_nop 1
	v_permlane16_swap_b32_e32 v48, v32
	v_add_f32_e32 v32, v32, v48
	s_nop 1
	v_add_f32_dpp v32, v32, v32 row_ror:8 row_mask:0xf bank_mask:0xf
	s_nop 1
	v_add_f32_dpp v32, v32, v32 row_ror:4 row_mask:0xf bank_mask:0xf
	s_nop 1
	v_add_f32_dpp v32, v32, v32 row_ror:2 row_mask:0xf bank_mask:0xf
	s_nop 1
	v_add_f32_dpp v32, v32, v32 row_ror:1 row_mask:0xf bank_mask:0xf
	v_mul_f32_e32 v33, v33, v33
	v_fmac_f32_e32 v33, v49, v49
	v_mov_b32_e32 v49, v33
	s_nop 1
	v_permlane16_swap_b32_e32 v49, v33
	v_add_f32_e32 v33, v33, v49
	s_nop 1
	v_add_f32_dpp v33, v33, v33 row_ror:8 row_mask:0xf bank_mask:0xf
	s_nop 1
	v_add_f32_dpp v33, v33, v33 row_ror:4 row_mask:0xf bank_mask:0xf
	s_nop 1
	v_add_f32_dpp v33, v33, v33 row_ror:2 row_mask:0xf bank_mask:0xf
	s_nop 1
	v_add_f32_dpp v33, v33, v33 row_ror:1 row_mask:0xf bank_mask:0xf
	v_mul_f32_e32 v34, v34, v34
	v_fmac_f32_e32 v34, v50, v50
	v_mov_b32_e32 v50, v34
	s_nop 1
	v_permlane16_swap_b32_e32 v50, v34
	v_add_f32_e32 v34, v34, v50
	s_nop 1
	v_add_f32_dpp v34, v34, v34 row_ror:8 row_mask:0xf bank_mask:0xf
	s_nop 1
	v_add_f32_dpp v34, v34, v34 row_ror:4 row_mask:0xf bank_mask:0xf
	s_nop 1
	v_add_f32_dpp v34, v34, v34 row_ror:2 row_mask:0xf bank_mask:0xf
	s_nop 1
	v_add_f32_dpp v34, v34, v34 row_ror:1 row_mask:0xf bank_mask:0xf
	v_mul_f32_e32 v35, v35, v35
	v_fmac_f32_e32 v35, v51, v51
	v_mov_b32_e32 v51, v35
	s_nop 1
	v_permlane16_swap_b32_e32 v51, v35
	v_add_f32_e32 v35, v35, v51
	s_nop 1
	v_add_f32_dpp v35, v35, v35 row_ror:8 row_mask:0xf bank_mask:0xf
	s_nop 1
	v_add_f32_dpp v35, v35, v35 row_ror:4 row_mask:0xf bank_mask:0xf
	s_nop 1
	v_add_f32_dpp v35, v35, v35 row_ror:2 row_mask:0xf bank_mask:0xf
	s_nop 1
	v_add_f32_dpp v35, v35, v35 row_ror:1 row_mask:0xf bank_mask:0xf
	v_mul_f32_e32 v36, v36, v36
	v_fmac_f32_e32 v36, v52, v52
	v_mov_b32_e32 v52, v36
	s_nop 1
	v_permlane16_swap_b32_e32 v52, v36
	v_add_f32_e32 v36, v36, v52
	s_nop 1
	v_add_f32_dpp v36, v36, v36 row_ror:8 row_mask:0xf bank_mask:0xf
	s_nop 1
	v_add_f32_dpp v36, v36, v36 row_ror:4 row_mask:0xf bank_mask:0xf
	s_nop 1
	v_add_f32_dpp v36, v36, v36 row_ror:2 row_mask:0xf bank_mask:0xf
	s_nop 1
	v_add_f32_dpp v36, v36, v36 row_ror:1 row_mask:0xf bank_mask:0xf
	v_mul_f32_e32 v37, v37, v37
	v_fmac_f32_e32 v37, v53, v53
	v_mov_b32_e32 v53, v37
	s_nop 1
	v_permlane16_swap_b32_e32 v53, v37
	v_add_f32_e32 v37, v37, v53
	s_nop 1
	v_add_f32_dpp v37, v37, v37 row_ror:8 row_mask:0xf bank_mask:0xf
	s_nop 1
	v_add_f32_dpp v37, v37, v37 row_ror:4 row_mask:0xf bank_mask:0xf
	s_nop 1
	v_add_f32_dpp v37, v37, v37 row_ror:2 row_mask:0xf bank_mask:0xf
	s_nop 1
	v_add_f32_dpp v37, v37, v37 row_ror:1 row_mask:0xf bank_mask:0xf
	v_mul_f32_e32 v38, v38, v38
	v_fmac_f32_e32 v38, v54, v54
	v_mov_b32_e32 v54, v38
	s_nop 1
	v_permlane16_swap_b32_e32 v54, v38
	v_add_f32_e32 v38, v38, v54
	s_nop 1
	v_add_f32_dpp v38, v38, v38 row_ror:8 row_mask:0xf bank_mask:0xf
	s_nop 1
	v_add_f32_dpp v38, v38, v38 row_ror:4 row_mask:0xf bank_mask:0xf
	s_nop 1
	v_add_f32_dpp v38, v38, v38 row_ror:2 row_mask:0xf bank_mask:0xf
	s_nop 1
	v_add_f32_dpp v38, v38, v38 row_ror:1 row_mask:0xf bank_mask:0xf
	v_mul_f32_e32 v39, v39, v39
	v_fmac_f32_e32 v39, v55, v55
	v_mov_b32_e32 v55, v39
	s_nop 1
	v_permlane16_swap_b32_e32 v55, v39
	v_add_f32_e32 v39, v39, v55
	s_nop 1
	v_add_f32_dpp v39, v39, v39 row_ror:8 row_mask:0xf bank_mask:0xf
	s_nop 1
	v_add_f32_dpp v39, v39, v39 row_ror:4 row_mask:0xf bank_mask:0xf
	s_nop 1
	v_add_f32_dpp v39, v39, v39 row_ror:2 row_mask:0xf bank_mask:0xf
	s_nop 1
	v_add_f32_dpp v39, v39, v39 row_ror:1 row_mask:0xf bank_mask:0xf
	v_mul_f32_e32 v40, v40, v40
	v_fmac_f32_e32 v40, v56, v56
	v_mov_b32_e32 v56, v40
	s_nop 1
	v_permlane16_swap_b32_e32 v56, v40
	v_add_f32_e32 v40, v40, v56
	s_nop 1
	v_add_f32_dpp v40, v40, v40 row_ror:8 row_mask:0xf bank_mask:0xf
	s_nop 1
	v_add_f32_dpp v40, v40, v40 row_ror:4 row_mask:0xf bank_mask:0xf
	s_nop 1
; DI int crow(int reg, int h) { return (reg & 3) + 8 * (reg >> 2) + 4 * h; }
; template <int MASK>
; __global__ void __launch_bounds__(256, 2) fwd_megakernel_t(Params p) {
;     ...
; #pragma unroll
;           for (int r = 0; r < 16; r++) {
;             float v = sq[r];
; #pragma unroll
;             for (int msk = 16; msk >= 1; msk >>= 1) v += __shfl_xor(v, msk);
;             if (cc == 0) rowsq[(size_t)(nt * 2 + wn) * T_ + m0 + wm * 64 + i * 32 + crow(r, hh)] = v;
;           }
	v_add_f32_dpp v40, v40, v40 row_ror:2 row_mask:0xf bank_mask:0xf
	s_nop 1
	v_add_f32_dpp v40, v40, v40 row_ror:1 row_mask:0xf bank_mask:0xf
	v_mul_f32_e32 v41, v41, v41
	v_fmac_f32_e32 v41, v57, v57
	v_mov_b32_e32 v57, v41
	s_nop 1
	v_permlane16_swap_b32_e32 v57, v41
	v_add_f32_e32 v41, v41, v57
	s_nop 1
	v_add_f32_dpp v41, v41, v41 row_ror:8 row_mask:0xf bank_mask:0xf
	s_nop 1
	v_add_f32_dpp v41, v41, v41 row_ror:4 row_mask:0xf bank_mask:0xf
	s_nop 1
	v_add_f32_dpp v41, v41, v41 row_ror:2 row_mask:0xf bank_mask:0xf
	s_nop 1
	v_add_f32_dpp v41, v41, v41 row_ror:1 row_mask:0xf bank_mask:0xf
	v_mul_f32_e32 v42, v42, v42
	v_fmac_f32_e32 v42, v58, v58
	v_mov_b32_e32 v58, v42
	s_nop 1
	v_permlane16_swap_b32_e32 v58, v42
	v_add_f32_e32 v42, v42, v58
	s_nop 1
	v_add_f32_dpp v42, v42, v42 row_ror:8 row_mask:0xf bank_mask:0xf
	s_nop 1
	v_add_f32_dpp v42, v42, v42 row_ror:4 row_mask:0xf bank_mask:0xf
	s_nop 1
	v_add_f32_dpp v42, v42, v42 row_ror:2 row_mask:0xf bank_mask:0xf
	s_nop 1
	v_add_f32_dpp v42, v42, v42 row_ror:1 row_mask:0xf bank_mask:0xf
	v_mul_f32_e32 v43, v43, v43
	v_fmac_f32_e32 v43, v59, v59
	v_mov_b32_e32 v59, v43
	s_nop 1
	v_permlane16_swap_b32_e32 v59, v43
	v_add_f32_e32 v43, v43, v59
	s_nop 1
	v_add_f32_dpp v43, v43, v43 row_ror:8 row_mask:0xf bank_mask:0xf
	s_nop 1
	v_add_f32_dpp v43, v43, v43 row_ror:4 row_mask:0xf bank_mask:0xf
	s_nop 1
	v_add_f32_dpp v43, v43, v43 row_ror:2 row_mask:0xf bank_mask:0xf
	s_nop 1
	v_add_f32_dpp v43, v43, v43 row_ror:1 row_mask:0xf bank_mask:0xf
	v_mul_f32_e32 v44, v44, v44
	v_fmac_f32_e32 v44, v60, v60
	v_mov_b32_e32 v60, v44
	s_nop 1
	v_permlane16_swap_b32_e32 v60, v44
	v_add_f32_e32 v44, v44, v60
	s_nop 1
	v_add_f32_dpp v44, v44, v44 row_ror:8 row_mask:0xf bank_mask:0xf
	s_nop 1
	v_add_f32_dpp v44, v44, v44 row_ror:4 row_mask:0xf bank_mask:0xf
	s_nop 1
	v_add_f32_dpp v44, v44, v44 row_ror:2 row_mask:0xf bank_mask:0xf
	s_nop 1
	v_add_f32_dpp v44, v44, v44 row_ror:1 row_mask:0xf bank_mask:0xf
	v_mul_f32_e32 v45, v45, v45
	v_fmac_f32_e32 v45, v61, v61
	v_mov_b32_e32 v61, v45
	s_nop 1
	v_permlane16_swap_b32_e32 v61, v45
	v_add_f32_e32 v45, v45, v61
	s_nop 1
	v_add_f32_dpp v45, v45, v45 row_ror:8 row_mask:0xf bank_mask:0xf
	s_nop 1
	v_add_f32_dpp v45, v45, v45 row_ror:4 row_mask:0xf bank_mask:0xf
	s_nop 1
	v_add_f32_dpp v45, v45, v45 row_ror:2 row_mask:0xf bank_mask:0xf
	s_nop 1
	v_add_f32_dpp v45, v45, v45 row_ror:1 row_mask:0xf bank_mask:0xf
	v_mul_f32_e32 v46, v46, v46
	v_fmac_f32_e32 v46, v62, v62
	v_mov_b32_e32 v62, v46
	s_nop 1
	v_permlane16_swap_b32_e32 v62, v46
	v_add_f32_e32 v46, v46, v62
	s_nop 1
	v_add_f32_dpp v46, v46, v46 row_ror:8 row_mask:0xf bank_mask:0xf
	s_nop 1
	v_add_f32_dpp v46, v46, v46 row_ror:4 row_mask:0xf bank_mask:0xf
	s_nop 1
	v_add_f32_dpp v46, v46, v46 row_ror:2 row_mask:0xf bank_mask:0xf
	s_nop 1
	v_add_f32_dpp v46, v46, v46 row_ror:1 row_mask:0xf bank_mask:0xf
	v_mul_f32_e32 v47, v47, v47
	v_fmac_f32_e32 v47, v63, v63
	v_mov_b32_e32 v63, v47
	s_nop 1
	v_permlane16_swap_b32_e32 v63, v47
	v_add_f32_e32 v47, v47, v63
	s_nop 1
	v_add_f32_dpp v47, v47, v47 row_ror:8 row_mask:0xf bank_mask:0xf
	s_nop 1
	v_add_f32_dpp v47, v47, v47 row_ror:4 row_mask:0xf bank_mask:0xf
	s_nop 1
	v_add_f32_dpp v47, v47, v47 row_ror:2 row_mask:0xf bank_mask:0xf
	s_nop 1
	v_add_f32_dpp v47, v47, v47 row_ror:1 row_mask:0xf bank_mask:0xf
	v_mul_f32_e32 v0, v0, v0
	v_fmac_f32_e32 v0, v16, v16
	v_mov_b32_e32 v16, v0
	s_nop 1
	v_permlane16_swap_b32_e32 v16, v0
	v_add_f32_e32 v0, v0, v16
	s_nop 1
	v_add_f32_dpp v0, v0, v0 row_ror:8 row_mask:0xf bank_mask:0xf
	s_nop 1
	v_add_f32_dpp v0, v0, v0 row_ror:4 row_mask:0xf bank_mask:0xf
	s_nop 1
	v_add_f32_dpp v0, v0, v0 row_ror:2 row_mask:0xf bank_mask:0xf
	s_nop 1
	v_add_f32_dpp v0, v0, v0 row_ror:1 row_mask:0xf bank_mask:0xf
	v_mul_f32_e32 v1, v1, v1
	v_fmac_f32_e32 v1, v17, v17
	v_mov_b32_e32 v17, v1
	s_nop 1
	v_permlane16_swap_b32_e32 v17, v1
	v_add_f32_e32 v1, v1, v17
	s_nop 1
	v_add_f32_dpp v1, v1, v1 row_ror:8 row_mask:0xf bank_mask:0xf
	s_nop 1
	v_add_f32_dpp v1, v1, v1 row_ror:4 row_mask:0xf bank_mask:0xf
	s_nop 1
	v_add_f32_dpp v1, v1, v1 row_ror:2 row_mask:0xf bank_mask:0xf
	s_nop 1
	v_add_f32_dpp v1, v1, v1 row_ror:1 row_mask:0xf bank_mask:0xf
	v_mul_f32_e32 v2, v2, v2
	v_fmac_f32_e32 v2, v18, v18
	v_mov_b32_e32 v18, v2
	s_nop 1
	v_permlane16_swap_b32_e32 v18, v2
	v_add_f32_e32 v2, v2, v18
	s_nop 1
	v_add_f32_dpp v2, v2, v2 row_ror:8 row_mask:0xf bank_mask:0xf
	s_nop 1
	v_add_f32_dpp v2, v2, v2 row_ror:4 row_mask:0xf bank_mask:0xf
	s_nop 1
	v_add_f32_dpp v2, v2, v2 row_ror:2 row_mask:0xf bank_mask:0xf
	s_nop 1
	v_add_f32_dpp v2, v2, v2 row_ror:1 row_mask:0xf bank_mask:0xf
	v_mul_f32_e32 v3, v3, v3
	v_fmac_f32_e32 v3, v19, v19
	v_mov_b32_e32 v19, v3
	s_nop 1
	v_permlane16_swap_b32_e32 v19, v3
	v_add_f32_e32 v3, v3, v19
	s_nop 1
	v_add_f32_dpp v3, v3, v3 row_ror:8 row_mask:0xf bank_mask:0xf
	s_nop 1
	v_add_f32_dpp v3, v3, v3 row_ror:4 row_mask:0xf bank_mask:0xf
	s_nop 1
	v_add_f32_dpp v3, v3, v3 row_ror:2 row_mask:0xf bank_mask:0xf
	s_nop 1
	v_add_f32_dpp v3, v3, v3 row_ror:1 row_mask:0xf bank_mask:0xf
	v_mul_f32_e32 v4, v4, v4
	v_fmac_f32_e32 v4, v20, v20
	v_mov_b32_e32 v20, v4
	s_nop 1
	v_permlane16_swap_b32_e32 v20, v4
	v_add_f32_e32 v4, v4, v20
	s_nop 1
	v_add_f32_dpp v4, v4, v4 row_ror:8 row_mask:0xf bank_mask:0xf
	s_nop 1
	v_add_f32_dpp v4, v4, v4 row_ror:4 row_mask:0xf bank_mask:0xf
	s_nop 1
	v_add_f32_dpp v4, v4, v4 row_ror:2 row_mask:0xf bank_mask:0xf
	s_nop 1
	v_add_f32_dpp v4, v4, v4 row_ror:1 row_mask:0xf bank_mask:0xf
	v_mul_f32_e32 v5, v5, v5
	v_fmac_f32_e32 v5, v21, v21
	v_mov_b32_e32 v21, v5
	s_nop 1
	v_permlane16_swap_b32_e32 v21, v5
; DI int crow(int reg, int h) { return (reg & 3) + 8 * (reg >> 2) + 4 * h; }
; template <int MASK>
; __global__ void __launch_bounds__(256, 2) fwd_megakernel_t(Params p) {
;     ...
; #pragma unroll
;           for (int r = 0; r < 16; r++) {
;             float v = sq[r];
; #pragma unroll
;             for (int msk = 16; msk >= 1; msk >>= 1) v += __shfl_xor(v, msk);
;             if (cc == 0) rowsq[(size_t)(nt * 2 + wn) * T_ + m0 + wm * 64 + i * 32 + crow(r, hh)] = v;
;           }
	v_add_f32_e32 v5, v5, v21
	s_nop 1
	v_add_f32_dpp v5, v5, v5 row_ror:8 row_mask:0xf bank_mask:0xf
	s_nop 1
	v_add_f32_dpp v5, v5, v5 row_ror:4 row_mask:0xf bank_mask:0xf
	s_nop 1
	v_add_f32_dpp v5, v5, v5 row_ror:2 row_mask:0xf bank_mask:0xf
	s_nop 1
	v_add_f32_dpp v5, v5, v5 row_ror:1 row_mask:0xf bank_mask:0xf
	v_mul_f32_e32 v6, v6, v6
	v_fmac_f32_e32 v6, v22, v22
	v_mov_b32_e32 v22, v6
	s_nop 1
	v_permlane16_swap_b32_e32 v22, v6
	v_add_f32_e32 v6, v6, v22
	s_nop 1
	v_add_f32_dpp v6, v6, v6 row_ror:8 row_mask:0xf bank_mask:0xf
	s_nop 1
	v_add_f32_dpp v6, v6, v6 row_ror:4 row_mask:0xf bank_mask:0xf
	s_nop 1
	v_add_f32_dpp v6, v6, v6 row_ror:2 row_mask:0xf bank_mask:0xf
	s_nop 1
	v_add_f32_dpp v6, v6, v6 row_ror:1 row_mask:0xf bank_mask:0xf
	v_mul_f32_e32 v7, v7, v7
	v_fmac_f32_e32 v7, v23, v23
	v_mov_b32_e32 v23, v7
	s_nop 1
	v_permlane16_swap_b32_e32 v23, v7
	v_add_f32_e32 v7, v7, v23
	s_nop 1
	v_add_f32_dpp v7, v7, v7 row_ror:8 row_mask:0xf bank_mask:0xf
	s_nop 1
	v_add_f32_dpp v7, v7, v7 row_ror:4 row_mask:0xf bank_mask:0xf
	s_nop 1
	v_add_f32_dpp v7, v7, v7 row_ror:2 row_mask:0xf bank_mask:0xf
	s_nop 1
	v_add_f32_dpp v7, v7, v7 row_ror:1 row_mask:0xf bank_mask:0xf
	v_mul_f32_e32 v8, v8, v8
	v_fmac_f32_e32 v8, v24, v24
	v_mov_b32_e32 v24, v8
	s_nop 1
	v_permlane16_swap_b32_e32 v24, v8
	v_add_f32_e32 v8, v8, v24
	s_nop 1
	v_add_f32_dpp v8, v8, v8 row_ror:8 row_mask:0xf bank_mask:0xf
	s_nop 1
	v_add_f32_dpp v8, v8, v8 row_ror:4 row_mask:0xf bank_mask:0xf
	s_nop 1
	v_add_f32_dpp v8, v8, v8 row_ror:2 row_mask:0xf bank_mask:0xf
	s_nop 1
	v_add_f32_dpp v8, v8, v8 row_ror:1 row_mask:0xf bank_mask:0xf
	v_mul_f32_e32 v9, v9, v9
	v_fmac_f32_e32 v9, v25, v25
	v_mov_b32_e32 v25, v9
	s_nop 1
	v_permlane16_swap_b32_e32 v25, v9
	v_add_f32_e32 v9, v9, v25
	s_nop 1
	v_add_f32_dpp v9, v9, v9 row_ror:8 row_mask:0xf bank_mask:0xf
	s_nop 1
	v_add_f32_dpp v9, v9, v9 row_ror:4 row_mask:0xf bank_mask:0xf
	s_nop 1
	v_add_f32_dpp v9, v9, v9 row_ror:2 row_mask:0xf bank_mask:0xf
	s_nop 1
	v_add_f32_dpp v9, v9, v9 row_ror:1 row_mask:0xf bank_mask:0xf
	v_mul_f32_e32 v10, v10, v10
	v_fmac_f32_e32 v10, v26, v26
	v_mov_b32_e32 v26, v10
	s_nop 1
	v_permlane16_swap_b32_e32 v26, v10
	v_add_f32_e32 v10, v10, v26
	s_nop 1
	v_add_f32_dpp v10, v10, v10 row_ror:8 row_mask:0xf bank_mask:0xf
	s_nop 1
	v_add_f32_dpp v10, v10, v10 row_ror:4 row_mask:0xf bank_mask:0xf
	s_nop 1
	v_add_f32_dpp v10, v10, v10 row_ror:2 row_mask:0xf bank_mask:0xf
	s_nop 1
	v_add_f32_dpp v10, v10, v10 row_ror:1 row_mask:0xf bank_mask:0xf
	v_mul_f32_e32 v11, v11, v11
	v_fmac_f32_e32 v11, v27, v27
	v_mov_b32_e32 v27, v11
	s_nop 1
	v_permlane16_swap_b32_e32 v27, v11
	v_add_f32_e32 v11, v11, v27
	s_nop 1
	v_add_f32_dpp v11, v11, v11 row_ror:8 row_mask:0xf bank_mask:0xf
	s_nop 1
	v_add_f32_dpp v11, v11, v11 row_ror:4 row_mask:0xf bank_mask:0xf
	s_nop 1
	v_add_f32_dpp v11, v11, v11 row_ror:2 row_mask:0xf bank_mask:0xf
	s_nop 1
	v_add_f32_dpp v11, v11, v11 row_ror:1 row_mask:0xf bank_mask:0xf
	v_mul_f32_e32 v12, v12, v12
	v_fmac_f32_e32 v12, v28, v28
	v_mov_b32_e32 v28, v12
	s_nop 1
	v_permlane16_swap_b32_e32 v28, v12
	v_add_f32_e32 v12, v12, v28
	s_nop 1
	v_add_f32_dpp v12, v12, v12 row_ror:8 row_mask:0xf bank_mask:0xf
	s_nop 1
	v_add_f32_dpp v12, v12, v12 row_ror:4 row_mask:0xf bank_mask:0xf
	s_nop 1
	v_add_f32_dpp v12, v12, v12 row_ror:2 row_mask:0xf bank_mask:0xf
	s_nop 1
	v_add_f32_dpp v12, v12, v12 row_ror:1 row_mask:0xf bank_mask:0xf
	v_mul_f32_e32 v13, v13, v13
	v_fmac_f32_e32 v13, v29, v29
	v_mov_b32_e32 v29, v13
	s_nop 1
	v_permlane16_swap_b32_e32 v29, v13
	v_add_f32_e32 v13, v13, v29
	s_nop 1
	v_add_f32_dpp v13, v13, v13 row_ror:8 row_mask:0xf bank_mask:0xf
	s_nop 1
	v_add_f32_dpp v13, v13, v13 row_ror:4 row_mask:0xf bank_mask:0xf
	s_nop 1
	v_add_f32_dpp v13, v13, v13 row_ror:2 row_mask:0xf bank_mask:0xf
	s_nop 1
	v_add_f32_dpp v13, v13, v13 row_ror:1 row_mask:0xf bank_mask:0xf
	v_mul_f32_e32 v14, v14, v14
	v_fmac_f32_e32 v14, v30, v30
	v_mov_b32_e32 v30, v14
	s_nop 1
	v_permlane16_swap_b32_e32 v30, v14
	v_add_f32_e32 v14, v14, v30
	s_nop 1
	v_add_f32_dpp v14, v14, v14 row_ror:8 row_mask:0xf bank_mask:0xf
	s_nop 1
	v_add_f32_dpp v14, v14, v14 row_ror:4 row_mask:0xf bank_mask:0xf
	s_nop 1
	v_add_f32_dpp v14, v14, v14 row_ror:2 row_mask:0xf bank_mask:0xf
	s_nop 1
	v_add_f32_dpp v14, v14, v14 row_ror:1 row_mask:0xf bank_mask:0xf
	v_mul_f32_e32 v15, v15, v15
	v_fmac_f32_e32 v15, v31, v31
	v_mov_b32_e32 v31, v15
	s_nop 1
	v_permlane16_swap_b32_e32 v31, v15
	v_add_f32_e32 v15, v15, v31
	s_nop 1
	v_add_f32_dpp v15, v15, v15 row_ror:8 row_mask:0xf bank_mask:0xf
	s_nop 1
	v_add_f32_dpp v15, v15, v15 row_ror:4 row_mask:0xf bank_mask:0xf
	s_nop 1
	v_add_f32_dpp v15, v15, v15 row_ror:2 row_mask:0xf bank_mask:0xf
	s_nop 1
	v_add_f32_dpp v15, v15, v15 row_ror:1 row_mask:0xf bank_mask:0xf
	s_and_saveexec_b64 s[6:7], s[4:5]
	global_store_dword v[146:147], v32, off
	global_store_dword v[146:147], v33, off offset:4
	global_store_dword v[146:147], v34, off offset:8
	global_store_dword v[146:147], v35, off offset:12
	global_store_dword v[146:147], v36, off offset:32
	global_store_dword v[146:147], v37, off offset:36
	global_store_dword v[146:147], v38, off offset:40
	global_store_dword v[146:147], v39, off offset:44
	global_store_dword v[146:147], v40, off offset:64
	global_store_dword v[146:147], v41, off offset:68
	global_store_dword v[146:147], v42, off offset:72
	global_store_dword v[146:147], v43, off offset:76
	global_store_dword v[146:147], v44, off offset:96
	global_store_dword v[146:147], v45, off offset:100
	global_store_dword v[146:147], v46, off offset:104
	global_store_dword v[146:147], v47, off offset:108
	global_store_dword v[146:147], v0, off offset:128
	global_store_dword v[146:147], v1, off offset:132
	global_store_dword v[146:147], v2, off offset:136
	global_store_dword v[146:147], v3, off offset:140
	global_store_dword v[146:147], v4, off offset:160
	global_store_dword v[146:147], v5, off offset:164
	global_store_dword v[146:147], v6, off offset:168
	global_store_dword v[146:147], v7, off offset:172
	global_store_dword v[146:147], v8, off offset:192
	global_store_dword v[146:147], v9, off offset:196
	global_store_dword v[146:147], v10, off offset:200
	global_store_dword v[146:147], v11, off offset:204
	global_store_dword v[146:147], v12, off offset:224
	global_store_dword v[146:147], v13, off offset:228
	global_store_dword v[146:147], v14, off offset:232
	global_store_dword v[146:147], v15, off offset:236
	s_or_b64 exec, exec, s[6:7]
	s_add_i32 s14, s14, 1

; template <int MODE>
; DI void attn_item(const u16* __restrict__ Qp, const u16* __restrict__ Kp, const u16* __restrict__ VTp, int q0,
;                   int kt_lo, int kt_hi, u16* __restrict__ Op, int os, float* __restrict__ lsep, int ls, char* lds, int tid) {
;     ...
;     for (int ks = 0; ks < NKS; ks++)
; #pragma unroll
;       for (int mt = 0; mt < NMT; mt++) {
;         const bf16x8 kf = *(const bf16x8*)(Ks + (mt * 32 + c) * KROW + (ks * 16 + h * 8) * 2);
;         st[mt] = MFMA32(kf, qf[ks], st[mt]);
;       }
;     if (NMT == 1) {
;       __builtin_amdgcn_sched_group_barrier(0x100, 3, 0);
; #pragma unroll
;       for (int ks = 0; ks < NKS - 3; ks++) {
;         __builtin_amdgcn_sched_group_barrier(0x008, 1, 0);
;         __builtin_amdgcn_sched_group_barrier(0x100, 1, 0);
;       }
;       __builtin_amdgcn_sched_group_barrier(0x008, 3, 0);
;     }
;     const int kb = kt * KT + 4 * h;
;     if (MODE == 0 && kt * KT + (KT - 1) <= q0 + wave * 32) {
;       float mx = st[0][0];
; #pragma unroll
;       for (int mt = 0; mt < NMT; mt++)
; #pragma unroll
;         for (int r = 0; r < 16; r++) mx = fmaxf(mx, st[mt][r]);
;       mx = fmaxf(mx, __shfl_xor(mx, 32));
;       const float m_new = fmaxf(m_run, mx);
;       const float alpha = __builtin_amdgcn_exp2f(m_run - m_new);
;       m_run = m_new;
;       float psum = 0.f;
; #pragma unroll
;       for (int mt = 0; mt < NMT; mt++)
; #pragma unroll
;         for (int r = 0; r < 16; r++) {
;           const float p = __builtin_amdgcn_exp2f(st[mt][r] - m_new);
;           psum += p;
;           st[mt][r] = p;
;         }
;       l_run = l_run * alpha + psum;
; #pragma unroll
;       for (int d = 0; d < 4; d++)
; #pragma unroll
;         for (int r = 0; r < 16; r++) ot[d][r] *= alpha;
;     } else if (MODE != 1) {
;       float mx = -1e30f;
; #pragma unroll
;       for (int mt = 0; mt < NMT; mt++)
; #pragma unroll
;         for (int r = 0; r < 16; r++) {
;           const int key = kb + mt * 32 + 8 * (r >> 2) + (r & 3);
;           const bool valid = (MODE == 0) ? (key <= myq) : (key <= myq && myq - key <= 128);
;           const float s = valid ? st[mt][r] : -1e30f;
;           st[mt][r] = s;
;           mx = fmaxf(mx, s);
;         }
;       mx = fmaxf(mx, __shfl_xor(mx, 32));
;       const float m_new = fmaxf(m_run, mx);
;       const float alpha = __builtin_amdgcn_exp2f(m_run - m_new);
;       m_run = m_new;
.LBB0_467:
	s_bitcmp1_b32 s42, 0
	s_cselect_b32 s11, 0x5a00, 0
	v_add3_u32 v200, s11, v210, v207
	v_add3_u32 v252, s11, v156, v208
	ds_read_b128 v[64:67], v200
	ds_read_b128 v[220:223], v200 offset:32
	ds_read_b128 v[236:239], v200 offset:64
	ds_read_b128 v[240:243], v200 offset:96
	ds_read_b128 v[244:247], v200 offset:128
	ds_read_b128 v[248:251], v200 offset:160
	s_add_i32 s14, s10, -1
	v_cmp_le_i32_e32 vcc, s14, v216
	s_waitcnt lgkmcnt(5)
	v_mfma_f32_32x32x16_bf16 v[64:79], v[64:67], v[80:83], 0
	s_waitcnt lgkmcnt(4)
	v_mfma_f32_32x32x16_bf16 v[64:79], v[220:223], v[84:87], v[64:79]
	ds_read_b128 v[220:223], v200 offset:192
	s_waitcnt lgkmcnt(4)
	v_mfma_f32_32x32x16_bf16 v[64:79], v[236:239], v[88:91], v[64:79]
	ds_read_b128 v[236:239], v200 offset:224
	s_waitcnt lgkmcnt(4)
	v_mfma_f32_32x32x16_bf16 v[64:79], v[240:243], v[92:95], v[64:79]
	ds_read_b128 v[240:243], v200 offset:256
	s_waitcnt lgkmcnt(4)
	v_mfma_f32_32x32x16_bf16 v[64:79], v[244:247], v[96:99], v[64:79]
	ds_read_b128 v[244:247], v200 offset:288
	s_waitcnt lgkmcnt(4)
	v_mfma_f32_32x32x16_bf16 v[64:79], v[248:251], v[100:103], v[64:79]
	ds_read_b128 v[248:251], v200 offset:320
	s_waitcnt lgkmcnt(4)
	v_mfma_f32_32x32x16_bf16 v[64:79], v[220:223], v[104:107], v[64:79]
	ds_read_b128 v[220:223], v200 offset:352
	s_waitcnt lgkmcnt(4)
	v_mfma_f32_32x32x16_bf16 v[64:79], v[236:239], v[108:111], v[64:79]
	s_waitcnt lgkmcnt(3)
	v_mfma_f32_32x32x16_bf16 v[64:79], v[240:243], v[112:115], v[64:79]
	s_waitcnt lgkmcnt(2)
	v_mfma_f32_32x32x16_bf16 v[64:79], v[244:247], v[116:119], v[64:79]
	s_waitcnt lgkmcnt(1)
	v_mfma_f32_32x32x16_bf16 v[64:79], v[248:251], v[120:123], v[64:79]
	s_waitcnt lgkmcnt(0)
	v_mfma_f32_32x32x16_bf16 v[64:79], v[220:223], v[124:127], v[64:79]
	ds_read_b64 v[236:237], v252 offset:12800
	ds_read_b64 v[238:239], v252 offset:12816
	ds_read_b64 v[240:241], v252 offset:15360
	ds_read_b64 v[242:243], v252 offset:15376
	ds_read_b64 v[244:245], v252 offset:17920
	ds_read_b64 v[246:247], v252 offset:17936
	ds_read_b64 v[248:249], v252 offset:20480
	ds_read_b64 v[250:251], v252 offset:20496
	s_and_saveexec_b64 s[14:15], vcc
	s_xor_b64 s[14:15], exec, s[14:15]
	s_cbranch_execz .LBB0_469
	s_nop 8
	v_max_f32_e32 v200, v65, v65
	v_max_f32_e32 v201, v64, v64
	v_max_f32_e32 v200, v201, v200
	v_max3_f32 v200, v200, v66, v67
	v_max3_f32 v200, v200, v68, v69
	v_max3_f32 v200, v200, v70, v71
	v_max3_f32 v200, v200, v72, v73
	v_max3_f32 v200, v200, v74, v75
	v_max3_f32 v200, v200, v76, v77
	v_max3_f32 v200, v200, v78, v79
	v_mov_b32_e32 v201, v200
	s_nop 1
	v_permlane32_swap_b32_e32 v201, v200
	v_max3_f32 v217, v218, v200, v201
	v_sub_f32_e32 v64, v64, v217
	v_exp_f32_e32 v219, v64
	v_sub_f32_e32 v64, v65, v217
	v_exp_f32_e32 v220, v64
	v_sub_f32_e32 v64, v66, v217
	v_exp_f32_e32 v221, v64
	v_sub_f32_e32 v64, v67, v217
	v_exp_f32_e32 v222, v64
	v_sub_f32_e32 v64, v68, v217
	v_exp_f32_e32 v223, v64
	v_sub_f32_e32 v64, v69, v217
	v_exp_f32_e32 v224, v64
	v_sub_f32_e32 v64, v70, v217
	v_exp_f32_e32 v225, v64
	v_sub_f32_e32 v64, v71, v217
	v_exp_f32_e32 v226, v64
	v_sub_f32_e32 v64, v72, v217
	v_exp_f32_e32 v227, v64
	v_sub_f32_e32 v64, v73, v217
	v_exp_f32_e32 v228, v64
	v_sub_f32_e32 v64, v74, v217
	v_exp_f32_e32 v229, v64
	v_sub_f32_e32 v64, v75, v217
	v_exp_f32_e32 v230, v64
	v_sub_f32_e32 v64, v76, v217
	v_exp_f32_e32 v231, v64
	v_sub_f32_e32 v64, v77, v217
	v_exp_f32_e32 v232, v64
	v_sub_f32_e32 v64, v78, v217
	v_exp_f32_e32 v233, v64
	v_sub_f32_e32 v64, v79, v217
	v_exp_f32_e32 v234, v64
.LBB0_469:
	s_andn2_saveexec_b64 s[14:15], s[14:15]
	s_cbranch_execz .LBB0_471
	v_add_u32_e32 v200, s10, v162
	v_subrev_u32_e32 v201, 32, v200
	v_cmp_le_i32_e32 vcc, v201, v168
	v_subrev_u32_e32 v217, 30, v200
	s_nop 2
	v_cndmask_b32_e32 v64, v197, v64, vcc
	v_cmp_lt_i32_e32 vcc, v201, v168
	s_nop 1
	v_cndmask_b32_e32 v65, v197, v65, vcc
	v_cmp_le_i32_e32 vcc, v217, v168
	v_subrev_u32_e32 v217, 29, v200
	v_max3_f32 v201, v64, s50, v65
	v_cndmask_b32_e32 v66, v197, v66, vcc
	v_cmp_le_i32_e32 vcc, v217, v168
	v_subrev_u32_e32 v217, 24, v200
	s_nop 0
	v_cndmask_b32_e32 v67, v197, v67, vcc
	v_cmp_le_i32_e32 vcc, v217, v168
	v_subrev_u32_e32 v217, 23, v200
	v_max3_f32 v201, v201, v66, v67
	v_cndmask_b32_e32 v68, v197, v68, vcc
	v_cmp_le_i32_e32 vcc, v217, v168
	v_subrev_u32_e32 v217, 22, v200
	s_nop 0
	v_cndmask_b32_e32 v69, v197, v69, vcc
	v_cmp_le_i32_e32 vcc, v217, v168
	v_subrev_u32_e32 v217, 21, v200
	v_max3_f32 v201, v201, v68, v69
	v_cndmask_b32_e32 v70, v197, v70, vcc
	v_cmp_le_i32_e32 vcc, v217, v168
	v_add_u32_e32 v217, -16, v200
	s_nop 0
	v_cndmask_b32_e32 v71, v197, v71, vcc
	v_cmp_le_i32_e32 vcc, v217, v168
	v_add_u32_e32 v217, -15, v200
	v_max3_f32 v201, v201, v70, v71
	v_cndmask_b32_e32 v72, v197, v72, vcc
	v_cmp_le_i32_e32 vcc, v217, v168
	v_add_u32_e32 v217, -14, v200
	s_nop 0
	v_cndmask_b32_e32 v73, v197, v73, vcc
	v_cmp_le_i32_e32 vcc, v217, v168
	v_add_u32_e32 v217, -13, v200
	v_max3_f32 v201, v201, v72, v73
	v_cndmask_b32_e32 v74, v197, v74, vcc
	v_cmp_le_i32_e32 vcc, v217, v168
	v_add_u32_e32 v217, -8, v200
	s_nop 0
	v_cndmask_b32_e32 v75, v197, v75, vcc
	v_cmp_le_i32_e32 vcc, v217, v168
	v_add_u32_e32 v217, -7, v200
	v_max3_f32 v201, v201, v74, v75
	v_cndmask_b32_e32 v76, v197, v76, vcc
	v_cmp_le_i32_e32 vcc, v217, v168
	v_add_u32_e32 v217, -6, v200
	v_add_u32_e32 v200, -5, v200
	v_cndmask_b32_e32 v77, v197, v77, vcc
	v_cmp_le_i32_e32 vcc, v217, v168
	v_max3_f32 v201, v201, v76, v77
	s_nop 0
	v_cndmask_b32_e32 v78, v197, v78, vcc
	v_cmp_le_i32_e32 vcc, v200, v168
	s_nop 1
	v_cndmask_b32_e32 v79, v197, v79, vcc
	v_max3_f32 v200, v201, v78, v79
	s_nop 0
	v_mov_b32_e32 v201, v200
; template <int MODE>
; DI void attn_item(const u16* __restrict__ Qp, const u16* __restrict__ Kp, const u16* __restrict__ VTp, int q0,
;                   int kt_lo, int kt_hi, u16* __restrict__ Op, int os, float* __restrict__ lsep, int ls, char* lds, int tid) {
;     ...
;     } else if (MODE != 1) {
;       float mx = -1e30f;
; #pragma unroll
;       for (int mt = 0; mt < NMT; mt++)
; #pragma unroll
;         for (int r = 0; r < 16; r++) {
;           const int key = kb + mt * 32 + 8 * (r >> 2) + (r & 3);
;           const bool valid = (MODE == 0) ? (key <= myq) : (key <= myq && myq - key <= 128);
;           const float s = valid ? st[mt][r] : -1e30f;
;           st[mt][r] = s;
;           mx = fmaxf(mx, s);
;         }
;       mx = fmaxf(mx, __shfl_xor(mx, 32));
;       const float m_new = fmaxf(m_run, mx);
;       const float alpha = __builtin_amdgcn_exp2f(m_run - m_new);
;       m_run = m_new;
;       float psum = 0.f;
; #pragma unroll
;       for (int mt = 0; mt < NMT; mt++)
; #pragma unroll
;         for (int r = 0; r < 16; r++) {
;           const float s = st[mt][r];
;           const float p = (s > -1e29f) ? __builtin_amdgcn_exp2f(s - m_new) : 0.f;
;           psum += p;
;           st[mt][r] = p;
;         }
;       l_run = l_run * alpha + psum;
; #pragma unroll
;       for (int d = 0; d < 4; d++)
; #pragma unroll
;         for (int r = 0; r < 16; r++) ot[d][r] *= alpha;
;     ...
; #pragma unroll
;     for (int s4 = 0; s4 < NS4; s4++) {
;       const int mt = s4 >> 1, r0 = (s4 & 1) * 8;
;       uint4 pw;
;       pw.x = pack2(st[mt][r0 + 0], st[mt][r0 + 1]);
;       pw.y = pack2(st[mt][r0 + 2], st[mt][r0 + 3]);
;       pw.z = pack2(st[mt][r0 + 4], st[mt][r0 + 5]);
;       pw.w = pack2(st[mt][r0 + 6], st[mt][r0 + 7]);
;       const bf16x8 pb = __builtin_bit_cast(bf16x8, pw);
; #pragma unroll
;       for (int dt = 0; dt < 4; dt++) {
;         const char* vr = Vs + (dt * 32 + c) * VROW + (16 * s4 + 4 * h) * 2;
;         const bf16x4 lo = *(const bf16x4*)(vr);
;         const bf16x4 hi = *(const bf16x4*)(vr + 16);
;         const bf16x8 vf = __builtin_shufflevector(lo, hi, 0, 1, 2, 3, 4, 5, 6, 7);
;         ot[dt] = MFMA32(vf, pb, ot[dt]);
;       }
;     }
;     if (MODE == 1) {
;       if (__syncthreads_and(R < -100.f)) break;
;     }
;     if (PF) {
;       if (it + 1 < ntiles) { PF_STORE((it + 1) & 1) }
;       __syncthreads();
;     }
;   }
	s_nop 1
	v_permlane32_swap_b32_e32 v201, v200
	v_cmp_lt_f32_e32 vcc, s33, v64
	v_max3_f32 v217, v218, v200, v201
	v_sub_f32_e32 v64, v64, v217
	v_exp_f32_e32 v64, v64
	s_nop 0
	v_cndmask_b32_e32 v219, 0, v64, vcc
	v_sub_f32_e32 v64, v65, v217
	v_exp_f32_e32 v64, v64
	v_cmp_lt_f32_e32 vcc, s33, v65
	s_nop 1
	v_cndmask_b32_e32 v220, 0, v64, vcc
	v_sub_f32_e32 v64, v66, v217
	v_exp_f32_e32 v64, v64
	v_cmp_lt_f32_e32 vcc, s33, v66
	s_nop 1
	v_cndmask_b32_e32 v221, 0, v64, vcc
	v_sub_f32_e32 v64, v67, v217
	v_exp_f32_e32 v64, v64
	v_cmp_lt_f32_e32 vcc, s33, v67
	s_nop 1
	v_cndmask_b32_e32 v222, 0, v64, vcc
	v_sub_f32_e32 v64, v68, v217
	v_exp_f32_e32 v64, v64
	v_cmp_lt_f32_e32 vcc, s33, v68
	s_nop 1
	v_cndmask_b32_e32 v223, 0, v64, vcc
	v_sub_f32_e32 v64, v69, v217
	v_exp_f32_e32 v64, v64
	v_cmp_lt_f32_e32 vcc, s33, v69
	s_nop 1
	v_cndmask_b32_e32 v224, 0, v64, vcc
	v_sub_f32_e32 v64, v70, v217
	v_exp_f32_e32 v64, v64
	v_cmp_lt_f32_e32 vcc, s33, v70
	s_nop 1
	v_cndmask_b32_e32 v225, 0, v64, vcc
	v_sub_f32_e32 v64, v71, v217
	v_exp_f32_e32 v64, v64
	v_cmp_lt_f32_e32 vcc, s33, v71
	s_nop 1
	v_cndmask_b32_e32 v226, 0, v64, vcc
	v_sub_f32_e32 v64, v72, v217
	v_exp_f32_e32 v64, v64
	v_cmp_lt_f32_e32 vcc, s33, v72
	s_nop 1
	v_cndmask_b32_e32 v227, 0, v64, vcc
	v_sub_f32_e32 v64, v73, v217
	v_exp_f32_e32 v64, v64
	v_cmp_lt_f32_e32 vcc, s33, v73
	s_nop 1
	v_cndmask_b32_e32 v228, 0, v64, vcc
	v_sub_f32_e32 v64, v74, v217
	v_exp_f32_e32 v64, v64
	v_cmp_lt_f32_e32 vcc, s33, v74
	s_nop 1
	v_cndmask_b32_e32 v229, 0, v64, vcc
	v_sub_f32_e32 v64, v75, v217
	v_exp_f32_e32 v64, v64
	v_cmp_lt_f32_e32 vcc, s33, v75
	s_nop 1
	v_cndmask_b32_e32 v230, 0, v64, vcc
	v_sub_f32_e32 v64, v76, v217
	v_exp_f32_e32 v64, v64
	v_cmp_lt_f32_e32 vcc, s33, v76
	s_nop 1
	v_cndmask_b32_e32 v231, 0, v64, vcc
	v_sub_f32_e32 v64, v77, v217
	v_exp_f32_e32 v64, v64
	v_cmp_lt_f32_e32 vcc, s33, v77
	s_nop 1
	v_cndmask_b32_e32 v232, 0, v64, vcc
	v_sub_f32_e32 v64, v78, v217
	v_exp_f32_e32 v64, v64
	v_cmp_lt_f32_e32 vcc, s33, v78
	s_nop 1
	v_cndmask_b32_e32 v233, 0, v64, vcc
	v_sub_f32_e32 v64, v79, v217
	v_exp_f32_e32 v64, v64
	v_cmp_lt_f32_e32 vcc, s33, v79
	s_nop 1
	v_cndmask_b32_e32 v234, 0, v64, vcc
.LBB0_471:
	s_or_b64 exec, exec, s[14:15]
	s_nop 5
	ds_read_b64 v[70:71], v252 offset:12832
	ds_read_b64 v[72:73], v252 offset:12848
	ds_read_b64 v[74:75], v252 offset:15392
	ds_read_b64 v[76:77], v252 offset:15408
	v_sub_f32_e32 v64, v218, v217
	v_exp_f32_e32 v68, v64
	v_cvt_pk_bf16_f32 v64, v219, v220
	v_cvt_pk_bf16_f32 v65, v221, v222
	v_cvt_pk_bf16_f32 v66, v223, v224
	v_cmp_neq_f32_e32 vcc, 1.0, v68
	s_cbranch_vccz .Lp4_noresc
	v_pk_mul_f32 v[62:63], v[62:63], v[68:69] op_sel_hi:[1,0]
	v_pk_mul_f32 v[60:61], v[60:61], v[68:69] op_sel_hi:[1,0]
	v_pk_mul_f32 v[58:59], v[58:59], v[68:69] op_sel_hi:[1,0]
	v_pk_mul_f32 v[56:57], v[56:57], v[68:69] op_sel_hi:[1,0]
	v_pk_mul_f32 v[54:55], v[54:55], v[68:69] op_sel_hi:[1,0]
	v_pk_mul_f32 v[52:53], v[52:53], v[68:69] op_sel_hi:[1,0]
	v_pk_mul_f32 v[50:51], v[50:51], v[68:69] op_sel_hi:[1,0]
	v_pk_mul_f32 v[48:49], v[48:49], v[68:69] op_sel_hi:[1,0]
	v_pk_mul_f32 v[46:47], v[46:47], v[68:69] op_sel_hi:[1,0]
	v_pk_mul_f32 v[44:45], v[44:45], v[68:69] op_sel_hi:[1,0]
	v_pk_mul_f32 v[42:43], v[42:43], v[68:69] op_sel_hi:[1,0]
	v_pk_mul_f32 v[40:41], v[40:41], v[68:69] op_sel_hi:[1,0]
	v_pk_mul_f32 v[38:39], v[38:39], v[68:69] op_sel_hi:[1,0]
	v_pk_mul_f32 v[36:37], v[36:37], v[68:69] op_sel_hi:[1,0]
	v_pk_mul_f32 v[34:35], v[34:35], v[68:69] op_sel_hi:[1,0]
	v_pk_mul_f32 v[32:33], v[32:33], v[68:69] op_sel_hi:[1,0]
	v_pk_mul_f32 v[30:31], v[30:31], v[68:69] op_sel_hi:[1,0]
	v_pk_mul_f32 v[28:29], v[28:29], v[68:69] op_sel_hi:[1,0]
	v_pk_mul_f32 v[26:27], v[26:27], v[68:69] op_sel_hi:[1,0]
	v_pk_mul_f32 v[24:25], v[24:25], v[68:69] op_sel_hi:[1,0]
	v_pk_mul_f32 v[22:23], v[22:23], v[68:69] op_sel_hi:[1,0]
	v_pk_mul_f32 v[20:21], v[20:21], v[68:69] op_sel_hi:[1,0]
	v_pk_mul_f32 v[18:19], v[18:19], v[68:69] op_sel_hi:[1,0]
	v_pk_mul_f32 v[16:17], v[16:17], v[68:69] op_sel_hi:[1,0]
	v_pk_mul_f32 v[14:15], v[14:15], v[68:69] op_sel_hi:[1,0]
	v_pk_mul_f32 v[12:13], v[12:13], v[68:69] op_sel_hi:[1,0]
	v_pk_mul_f32 v[10:11], v[10:11], v[68:69] op_sel_hi:[1,0]
	v_pk_mul_f32 v[8:9], v[8:9], v[68:69] op_sel_hi:[1,0]
	v_pk_mul_f32 v[6:7], v[6:7], v[68:69] op_sel_hi:[1,0]
	v_pk_mul_f32 v[4:5], v[4:5], v[68:69] op_sel_hi:[1,0]
	v_pk_mul_f32 v[2:3], v[2:3], v[68:69] op_sel_hi:[1,0]
	v_pk_mul_f32 v[0:1], v[0:1], v[68:69] op_sel_hi:[1,0]
.Lp4_noresc:
.Lp4_pv:
	v_cvt_pk_bf16_f32 v67, v225, v226
	s_add_i32 s42, s42, 1
	s_andn2_b64 vcc, exec, s[12:13]
	s_waitcnt lgkmcnt(4)
	s_nop 0
	v_mfma_f32_32x32x16_bf16 v[48:63], v[236:239], v[64:67], v[48:63]
	ds_read_b64 v[236:237], v252 offset:17952
	ds_read_b64 v[238:239], v252 offset:17968
	v_mfma_f32_32x32x16_bf16 v[32:47], v[240:243], v[64:67], v[32:47]
	ds_read_b64 v[240:241], v252 offset:20512
	ds_read_b64 v[242:243], v252 offset:20528
	v_mfma_f32_32x32x16_bf16 v[16:31], v[244:247], v[64:67], v[16:31]
	v_mfma_f32_32x32x16_bf16 v[0:15], v[248:251], v[64:67], v[0:15]
	v_cvt_pk_bf16_f32 v64, v227, v228
	v_cvt_pk_bf16_f32 v65, v229, v230
	v_cvt_pk_bf16_f32 v66, v231, v232
	v_cvt_pk_bf16_f32 v67, v233, v234
	s_waitcnt lgkmcnt(4)
	s_nop 0
	v_mfma_f32_32x32x16_bf16 v[32:47], v[74:77], v[64:67], v[32:47]
	s_waitcnt lgkmcnt(2)
	v_mfma_f32_32x32x16_bf16 v[16:31], v[236:239], v[64:67], v[16:31]
	v_mfma_f32_32x32x16_bf16 v[48:63], v[70:73], v[64:67], v[48:63]
	s_waitcnt lgkmcnt(0)
	v_mfma_f32_32x32x16_bf16 v[0:15], v[240:243], v[64:67], v[0:15]
	s_cbranch_vccnz .LBB0_473
	s_bitcmp1_b32 s42, 0
	s_cselect_b32 s11, 0x5a00, 0
	v_add3_u32 v64, s11, v209, v174
	s_waitcnt vmcnt(4)
	ds_write_b128 v64, v[128:131]
	s_waitcnt vmcnt(3)
	ds_write_b128 v64, v[132:135] offset:128
	s_waitcnt vmcnt(2)
	ds_write_b128 v64, v[136:139] offset:256
	v_add3_u32 v64, s11, v177, v175
	s_waitcnt vmcnt(1)
	ds_write_b128 v64, v[140:143] offset:12800
	s_waitcnt vmcnt(0)
	ds_write_b128 v64, v[144:147] offset:17920

; DI float bflo(unsigned v) { return __uint_as_float(v << 16); }
; DI float bfhi(unsigned v) { return __uint_as_float(v & 0xffff0000u); }
; template <int MASK>
; __global__ void __launch_bounds__(256, 2) fwd_megakernel_t(Params p) {
;     ...
;         __syncthreads();
;         {
;           const int l8 = tid & 7;
; #pragma unroll
;           for (int ps = 0; ps < 4; ps++) {
;             const int row = (tid >> 3) + 32 * ps;
;             const u16* ar = A + (size_t)(m0 + row) * NPJ + l8 * 8;
;             float ss = 0.f;
;             for (int k = 0; k < Kd; k += 64) {
;               const uint4 v = *(const uint4*)(ar + k);
;               ss += bflo(v.x) * bflo(v.x) + bfhi(v.x) * bfhi(v.x) + bflo(v.y) * bflo(v.y) + bfhi(v.y) * bfhi(v.y) +
;                     bflo(v.z) * bflo(v.z) + bfhi(v.z) * bfhi(v.z) + bflo(v.w) * bflo(v.w) + bfhi(v.w) * bfhi(v.w);
;             }
;             ss += __shfl_xor(ss, 1);
;             ss += __shfl_xor(ss, 2);
;             ss += __shfl_xor(ss, 4);
;             if (l8 == 0) s_rinv[row] = rsqrtf(ss / (float)Kd + EPS_);
;           }
;         }
.LBB0_495:
	s_andn2_b64 vcc, exec, s[6:7]
	s_mov_b32 s12, 38
	s_cbranch_vccnz .LBB0_552
	s_cmp_gt_i32 s29, 20
	s_mov_b32 s12, 40
	s_cbranch_scc1 .LBB0_552
	s_lshl_b32 s26, s28, 7
	s_cmp_gt_i32 s29, 8
	s_cselect_b64 s[6:7], -1, 0
	s_cmp_lt_i32 s29, 9
	s_cselect_b64 s[12:13], -1, 0
	s_and_b64 s[8:9], s[12:13], exec
	s_movk_i32 s8, 0x100
	s_cselect_b32 s24, 0x200, s8
	s_movk_i32 s8, 0xf00
	s_cselect_b32 s14, s8, 0x1100
	s_lshl_b32 s50, s14, 1
	v_add_u32_e32 v14, s26, v128
	v_mov_b64_e32 v[0:1], s[50:51]
	v_mad_i64_i32 v[0:1], s[30:31], v14, s69, v[0:1]
	s_mov_b32 s8, 0
	v_mad_i64_i32 v[2:3], s[30:31], v14, s69, 0
	v_lshl_add_u64 v[4:5], v[140:141], 0, v[0:1]
	v_mov_b32_e32 v6, 0
	s_barrier
	v_add_co_u32_e32 v84, vcc, 0x4a000, v4
	s_nop 1
	v_addc_co_u32_e32 v85, vcc, 0, v5, vcc
	v_add_co_u32_e32 v86, vcc, 0x94000, v4
	s_nop 1
	v_addc_co_u32_e32 v87, vcc, 0, v5, vcc
	v_add_co_u32_e32 v88, vcc, 0xde000, v4
	s_nop 1
	v_addc_co_u32_e32 v89, vcc, 0, v5, vcc
	v_mov_b32_e32 v34, 0
	v_mov_b32_e32 v35, 0
	v_mov_b32_e32 v36, 0
	v_mov_b32_e32 v37, 0
	global_load_dwordx4 v[40:43], v[4:5], off offset:-8
	global_load_dwordx4 v[44:47], v[84:85], off offset:-8
	global_load_dwordx4 v[48:51], v[86:87], off offset:-8
	global_load_dwordx4 v[52:55], v[88:89], off offset:-8
.Lp2r_loop:
	global_load_dwordx4 v[56:59], v[4:5], off offset:120
	global_load_dwordx4 v[60:63], v[84:85], off offset:120
	global_load_dwordx4 v[64:67], v[86:87], off offset:120
	global_load_dwordx4 v[68:71], v[88:89], off offset:120
	s_waitcnt vmcnt(4)
	v_lshlrev_b32_e32 v72, 16, v40
	v_and_b32_e32 v73, 0xffff0000, v40
	v_lshlrev_b32_e32 v75, 16, v41
	v_and_b32_e32 v74, 0xffff0000, v41
	v_lshlrev_b32_e32 v77, 16, v42
	v_and_b32_e32 v76, 0xffff0000, v42
	v_lshlrev_b32_e32 v79, 16, v43
	v_and_b32_e32 v78, 0xffff0000, v43
	v_pk_mul_f32 v[72:73], v[72:73], v[72:73]
	v_pk_mul_f32 v[74:75], v[74:75], v[74:75]
	v_add_f32_e32 v80, v72, v73
	v_add_f32_e32 v80, v80, v75
	v_pk_mul_f32 v[76:77], v[76:77], v[76:77]
	v_add_f32_e32 v80, v74, v80
	v_add_f32_e32 v80, v77, v80
	v_pk_mul_f32 v[78:79], v[78:79], v[78:79]
	v_add_f32_e32 v80, v76, v80
	v_add_f32_e32 v80, v79, v80
	v_add_f32_e32 v80, v78, v80
	v_add_f32_e32 v34, v34, v80
	v_lshlrev_b32_e32 v72, 16, v44
	v_and_b32_e32 v73, 0xffff0000, v44
	v_lshlrev_b32_e32 v75, 16, v45
	v_and_b32_e32 v74, 0xffff0000, v45
	v_lshlrev_b32_e32 v77, 16, v46
	v_and_b32_e32 v76, 0xffff0000, v46
	v_lshlrev_b32_e32 v79, 16, v47
	v_and_b32_e32 v78, 0xffff0000, v47
	v_pk_mul_f32 v[72:73], v[72:73], v[72:73]
	v_pk_mul_f32 v[74:75], v[74:75], v[74:75]
	v_add_f32_e32 v80, v72, v73
	v_add_f32_e32 v80, v80, v75
	v_pk_mul_f32 v[76:77], v[76:77], v[76:77]
	v_add_f32_e32 v80, v74, v80
	v_add_f32_e32 v80, v77, v80
	v_pk_mul_f32 v[78:79], v[78:79], v[78:79]
	v_add_f32_e32 v80, v76, v80
	v_add_f32_e32 v80, v79, v80
	v_add_f32_e32 v80, v78, v80
	v_add_f32_e32 v35, v35, v80
	v_lshlrev_b32_e32 v72, 16, v48
	v_and_b32_e32 v73, 0xffff0000, v48
	v_lshlrev_b32_e32 v75, 16, v49
	v_and_b32_e32 v74, 0xffff0000, v49
	v_lshlrev_b32_e32 v77, 16, v50
	v_and_b32_e32 v76, 0xffff0000, v50
	v_lshlrev_b32_e32 v79, 16, v51
	v_and_b32_e32 v78, 0xffff0000, v51
	v_pk_mul_f32 v[72:73], v[72:73], v[72:73]
	v_pk_mul_f32 v[74:75], v[74:75], v[74:75]
	v_add_f32_e32 v80, v72, v73
	v_add_f32_e32 v80, v80, v75
	v_pk_mul_f32 v[76:77], v[76:77], v[76:77]
	v_add_f32_e32 v80, v74, v80
	v_add_f32_e32 v80, v77, v80
	v_pk_mul_f32 v[78:79], v[78:79], v[78:79]
	v_add_f32_e32 v80, v76, v80
	v_add_f32_e32 v80, v79, v80
	v_add_f32_e32 v80, v78, v80
	v_add_f32_e32 v36, v36, v80
	v_lshlrev_b32_e32 v72, 16, v52
	v_and_b32_e32 v73, 0xffff0000, v52
	v_lshlrev_b32_e32 v75, 16, v53
	v_and_b32_e32 v74, 0xffff0000, v53
	v_lshlrev_b32_e32 v77, 16, v54
	v_and_b32_e32 v76, 0xffff0000, v54
	v_lshlrev_b32_e32 v79, 16, v55
	v_and_b32_e32 v78, 0xffff0000, v55
	v_pk_mul_f32 v[72:73], v[72:73], v[72:73]
	v_pk_mul_f32 v[74:75], v[74:75], v[74:75]
	v_add_f32_e32 v80, v72, v73
	v_add_f32_e32 v80, v80, v75
	v_pk_mul_f32 v[76:77], v[76:77], v[76:77]
	v_add_f32_e32 v80, v74, v80
	v_add_f32_e32 v80, v77, v80
	v_pk_mul_f32 v[78:79], v[78:79], v[78:79]
	v_add_f32_e32 v80, v76, v80
	v_add_f32_e32 v80, v79, v80
	v_add_f32_e32 v80, v78, v80
	v_add_f32_e32 v37, v37, v80
	global_load_dwordx4 v[40:43], v[4:5], off offset:248
	global_load_dwordx4 v[44:47], v[84:85], off offset:248
	global_load_dwordx4 v[48:51], v[86:87], off offset:248
	global_load_dwordx4 v[52:55], v[88:89], off offset:248
	s_waitcnt vmcnt(4)
; DI float bflo(unsigned v) { return __uint_as_float(v << 16); }
; DI float bfhi(unsigned v) { return __uint_as_float(v & 0xffff0000u); }
; template <int MASK>
; __global__ void __launch_bounds__(256, 2) fwd_megakernel_t(Params p) {
;     ...
;         __syncthreads();
;         {
;           const int l8 = tid & 7;
; #pragma unroll
;           for (int ps = 0; ps < 4; ps++) {
;             const int row = (tid >> 3) + 32 * ps;
;             const u16* ar = A + (size_t)(m0 + row) * NPJ + l8 * 8;
;             float ss = 0.f;
;             for (int k = 0; k < Kd; k += 64) {
;               const uint4 v = *(const uint4*)(ar + k);
;               ss += bflo(v.x) * bflo(v.x) + bfhi(v.x) * bfhi(v.x) + bflo(v.y) * bflo(v.y) + bfhi(v.y) * bfhi(v.y) +
;                     bflo(v.z) * bflo(v.z) + bfhi(v.z) * bfhi(v.z) + bflo(v.w) * bflo(v.w) + bfhi(v.w) * bfhi(v.w);
;             }
;             ss += __shfl_xor(ss, 1);
;             ss += __shfl_xor(ss, 2);
;             ss += __shfl_xor(ss, 4);
;             if (l8 == 0) s_rinv[row] = rsqrtf(ss / (float)Kd + EPS_);
;           }
;         }
	v_lshlrev_b32_e32 v72, 16, v56
	v_and_b32_e32 v73, 0xffff0000, v56
	v_lshlrev_b32_e32 v75, 16, v57
	v_and_b32_e32 v74, 0xffff0000, v57
	v_lshlrev_b32_e32 v77, 16, v58
	v_and_b32_e32 v76, 0xffff0000, v58
	v_lshlrev_b32_e32 v79, 16, v59
	v_and_b32_e32 v78, 0xffff0000, v59
	v_pk_mul_f32 v[72:73], v[72:73], v[72:73]
	v_pk_mul_f32 v[74:75], v[74:75], v[74:75]
	v_add_f32_e32 v80, v72, v73
	v_add_f32_e32 v80, v80, v75
	v_pk_mul_f32 v[76:77], v[76:77], v[76:77]
	v_add_f32_e32 v80, v74, v80
	v_add_f32_e32 v80, v77, v80
	v_pk_mul_f32 v[78:79], v[78:79], v[78:79]
	v_add_f32_e32 v80, v76, v80
	v_add_f32_e32 v80, v79, v80
	v_add_f32_e32 v80, v78, v80
	v_add_f32_e32 v34, v34, v80
	v_lshlrev_b32_e32 v72, 16, v60
	v_and_b32_e32 v73, 0xffff0000, v60
	v_lshlrev_b32_e32 v75, 16, v61
	v_and_b32_e32 v74, 0xffff0000, v61
	v_lshlrev_b32_e32 v77, 16, v62
	v_and_b32_e32 v76, 0xffff0000, v62
	v_lshlrev_b32_e32 v79, 16, v63
	v_and_b32_e32 v78, 0xffff0000, v63
	v_pk_mul_f32 v[72:73], v[72:73], v[72:73]
	v_pk_mul_f32 v[74:75], v[74:75], v[74:75]
	v_add_f32_e32 v80, v72, v73
	v_add_f32_e32 v80, v80, v75
	v_pk_mul_f32 v[76:77], v[76:77], v[76:77]
	v_add_f32_e32 v80, v74, v80
	v_add_f32_e32 v80, v77, v80
	v_pk_mul_f32 v[78:79], v[78:79], v[78:79]
	v_add_f32_e32 v80, v76, v80
	v_add_f32_e32 v80, v79, v80
	v_add_f32_e32 v80, v78, v80
	v_add_f32_e32 v35, v35, v80
	v_lshlrev_b32_e32 v72, 16, v64
	v_and_b32_e32 v73, 0xffff0000, v64
	v_lshlrev_b32_e32 v75, 16, v65
	v_and_b32_e32 v74, 0xffff0000, v65
	v_lshlrev_b32_e32 v77, 16, v66
	v_and_b32_e32 v76, 0xffff0000, v66
	v_lshlrev_b32_e32 v79, 16, v67
	v_and_b32_e32 v78, 0xffff0000, v67
	v_pk_mul_f32 v[72:73], v[72:73], v[72:73]
	v_pk_mul_f32 v[74:75], v[74:75], v[74:75]
	v_add_f32_e32 v80, v72, v73
	v_add_f32_e32 v80, v80, v75
	v_pk_mul_f32 v[76:77], v[76:77], v[76:77]
	v_add_f32_e32 v80, v74, v80
	v_add_f32_e32 v80, v77, v80
	v_pk_mul_f32 v[78:79], v[78:79], v[78:79]
	v_add_f32_e32 v80, v76, v80
	v_add_f32_e32 v80, v79, v80
	v_add_f32_e32 v80, v78, v80
	v_add_f32_e32 v36, v36, v80
	v_lshlrev_b32_e32 v72, 16, v68
	v_and_b32_e32 v73, 0xffff0000, v68
	v_lshlrev_b32_e32 v75, 16, v69
	v_and_b32_e32 v74, 0xffff0000, v69
	v_lshlrev_b32_e32 v77, 16, v70
	v_and_b32_e32 v76, 0xffff0000, v70
	v_lshlrev_b32_e32 v79, 16, v71
	v_and_b32_e32 v78, 0xffff0000, v71
	v_pk_mul_f32 v[72:73], v[72:73], v[72:73]
	v_pk_mul_f32 v[74:75], v[74:75], v[74:75]
	v_add_f32_e32 v80, v72, v73
	v_add_f32_e32 v80, v80, v75
	v_pk_mul_f32 v[76:77], v[76:77], v[76:77]
	v_add_f32_e32 v80, v74, v80
	v_add_f32_e32 v80, v77, v80
	v_pk_mul_f32 v[78:79], v[78:79], v[78:79]
	v_add_f32_e32 v80, v76, v80
	v_add_f32_e32 v80, v79, v80
	v_add_f32_e32 v80, v78, v80
	v_add_f32_e32 v37, v37, v80
	v_lshl_add_u64 v[4:5], v[4:5], 0, s[66:67]
	v_lshl_add_u64 v[84:85], v[84:85], 0, s[66:67]
	v_lshl_add_u64 v[86:87], v[86:87], 0, s[66:67]
	v_lshl_add_u64 v[88:89], v[88:89], 0, s[66:67]
	s_add_i32 s8, s8, 0x80
	s_cmp_lt_u32 s8, s24
	s_cbranch_scc1 .Lp2r_loop
	s_waitcnt vmcnt(0)
	v_mov_b32_e32 v6, v34
	v_cmp_lt_i32_e32 vcc, v194, v189
	v_cvt_f32_u32_e32 v18, s24
	s_nop 0
	v_cndmask_b32_e32 v4, v187, v194, vcc
	v_lshlrev_b32_e32 v19, 2, v4
	ds_bpermute_b32 v4, v19, v6
	v_cmp_lt_i32_e32 vcc, v193, v189
	s_waitcnt lgkmcnt(0)
	v_add_f32_e32 v4, v6, v4
	v_cndmask_b32_e32 v5, v187, v193, vcc
	v_lshlrev_b32_e32 v20, 2, v5
	ds_bpermute_b32 v5, v20, v4
	v_cmp_lt_i32_e32 vcc, v192, v189
	s_waitcnt lgkmcnt(0)
	v_add_f32_e32 v4, v4, v5
	v_cndmask_b32_e32 v6, v187, v192, vcc
	v_lshlrev_b32_e32 v21, 2, v6
	ds_bpermute_b32 v5, v21, v4
	s_and_saveexec_b64 s[8:9], s[4:5]
	s_cbranch_execz .LBB0_501
	s_waitcnt lgkmcnt(0)
	v_add_f32_e32 v4, v4, v5
	v_div_scale_f32 v5, s[30:31], v18, v18, v4
	v_rcp_f32_e32 v6, v5
	v_div_scale_f32 v7, vcc, v4, v18, v4
	v_fma_f32 v8, -v5, v6, 1.0
	v_fmac_f32_e32 v6, v8, v6
	v_mul_f32_e32 v8, v7, v6
	v_fma_f32 v9, -v5, v8, v7
	v_fmac_f32_e32 v8, v9, v6
	v_fma_f32 v5, -v5, v8, v7
	v_div_fmas_f32 v5, v5, v6, v8
	v_div_fixup_f32 v4, v5, v18, v4
	v_add_f32_e32 v4, 0x358637bd, v4
	v_mul_f32_e32 v5, 0x4b800000, v4
	v_cmp_gt_f32_e32 vcc, s62, v4
	s_nop 1
	v_cndmask_b32_e32 v4, v4, v5, vcc
	v_rsq_f32_e32 v4, v4
	s_nop 0
	v_mul_f32_e32 v5, 0x45800000, v4
	v_cndmask_b32_e32 v4, v4, v5, vcc
	ds_write_b32 v153, v4
; DI float bflo(unsigned v) { return __uint_as_float(v << 16); }
; DI float bfhi(unsigned v) { return __uint_as_float(v & 0xffff0000u); }
; template <int MASK>
; __global__ void __launch_bounds__(256, 2) fwd_megakernel_t(Params p) {
;     ...
;           for (int ps = 0; ps < 4; ps++) {
;             const int row = (tid >> 3) + 32 * ps;
;             const u16* ar = A + (size_t)(m0 + row) * NPJ + l8 * 8;
;             float ss = 0.f;
;             for (int k = 0; k < Kd; k += 64) {
;               const uint4 v = *(const uint4*)(ar + k);
;               ss += bflo(v.x) * bflo(v.x) + bfhi(v.x) * bfhi(v.x) + bflo(v.y) * bflo(v.y) + bfhi(v.y) * bfhi(v.y) +
;                     bflo(v.z) * bflo(v.z) + bfhi(v.z) * bfhi(v.z) + bflo(v.w) * bflo(v.w) + bfhi(v.w) * bfhi(v.w);
;             }
;             ss += __shfl_xor(ss, 1);
;             ss += __shfl_xor(ss, 2);
;             ss += __shfl_xor(ss, 4);
;             if (l8 == 0) s_rinv[row] = rsqrtf(ss / (float)Kd + EPS_);
;           }
.LBB0_501:
	s_or_b64 exec, exec, s[8:9]
	v_add_u32_e32 v8, 32, v14
	s_waitcnt lgkmcnt(0)
	v_mov_b64_e32 v[4:5], s[50:51]
	v_mad_i64_i32 v[6:7], s[8:9], v8, s69, 0
	v_mad_i64_i32 v[4:5], s[8:9], v8, s69, v[4:5]
	v_lshl_add_u64 v[8:9], v[140:141], 0, v[4:5]
	s_mov_b32 s8, 0
	v_mov_b32_e32 v10, 0
	v_mov_b32_e32 v10, v35
	ds_bpermute_b32 v8, v19, v10
	s_waitcnt lgkmcnt(0)
	v_add_f32_e32 v8, v10, v8
	ds_bpermute_b32 v9, v20, v8
	s_waitcnt lgkmcnt(0)
	v_add_f32_e32 v8, v8, v9
	ds_bpermute_b32 v9, v21, v8
	s_and_saveexec_b64 s[8:9], s[4:5]
	s_cbranch_execz .LBB0_505
	s_waitcnt lgkmcnt(0)
	v_add_f32_e32 v8, v8, v9
	v_div_scale_f32 v9, s[30:31], v18, v18, v8
	v_rcp_f32_e32 v10, v9
	v_div_scale_f32 v11, vcc, v8, v18, v8
	v_fma_f32 v12, -v9, v10, 1.0
	v_fmac_f32_e32 v10, v12, v10
	v_mul_f32_e32 v12, v11, v10
	v_fma_f32 v13, -v9, v12, v11
	v_fmac_f32_e32 v12, v13, v10
	v_fma_f32 v9, -v9, v12, v11
	v_div_fmas_f32 v9, v9, v10, v12
	v_div_fixup_f32 v8, v9, v18, v8
	v_add_f32_e32 v8, 0x358637bd, v8
	v_mul_f32_e32 v9, 0x4b800000, v8
	v_cmp_gt_f32_e32 vcc, s62, v8
	s_nop 1
	v_cndmask_b32_e32 v8, v8, v9, vcc
	v_rsq_f32_e32 v8, v8
	s_nop 0
	v_mul_f32_e32 v9, 0x45800000, v8
	v_cndmask_b32_e32 v8, v8, v9, vcc
	ds_write_b32 v153, v8 offset:128
.LBB0_505:
	s_or_b64 exec, exec, s[8:9]
	v_add_u32_e32 v12, 64, v14
	s_waitcnt lgkmcnt(0)
	v_mov_b64_e32 v[8:9], s[50:51]
	v_mad_i64_i32 v[10:11], s[8:9], v12, s69, 0
	v_mad_i64_i32 v[8:9], s[8:9], v12, s69, v[8:9]
	v_lshl_add_u64 v[12:13], v[140:141], 0, v[8:9]
	s_mov_b32 s8, 0
	v_mov_b32_e32 v15, 0
	v_mov_b32_e32 v15, v36
	ds_bpermute_b32 v12, v19, v15
	s_waitcnt lgkmcnt(0)
	v_add_f32_e32 v12, v15, v12
	ds_bpermute_b32 v13, v20, v12
	s_waitcnt lgkmcnt(0)
	v_add_f32_e32 v12, v12, v13
	ds_bpermute_b32 v13, v21, v12
	s_and_saveexec_b64 s[8:9], s[4:5]
	s_cbranch_execz .LBB0_509
	s_waitcnt lgkmcnt(0)
	v_add_f32_e32 v12, v12, v13
	v_div_scale_f32 v13, s[30:31], v18, v18, v12
	v_rcp_f32_e32 v15, v13
	v_div_scale_f32 v16, vcc, v12, v18, v12
	v_fma_f32 v17, -v13, v15, 1.0
	v_fmac_f32_e32 v15, v17, v15
	v_mul_f32_e32 v17, v16, v15
	v_fma_f32 v22, -v13, v17, v16
	v_fmac_f32_e32 v17, v22, v15
	v_fma_f32 v13, -v13, v17, v16
	v_div_fmas_f32 v13, v13, v15, v17
	v_div_fixup_f32 v12, v13, v18, v12
	v_add_f32_e32 v12, 0x358637bd, v12
	v_mul_f32_e32 v13, 0x4b800000, v12
	v_cmp_gt_f32_e32 vcc, s62, v12
	s_nop 1
	v_cndmask_b32_e32 v12, v12, v13, vcc
	v_rsq_f32_e32 v12, v12
	s_nop 0
	v_mul_f32_e32 v13, 0x45800000, v12
	v_cndmask_b32_e32 v12, v12, v13, vcc
	ds_write_b32 v153, v12 offset:256
.LBB0_509:
	s_or_b64 exec, exec, s[8:9]
	v_add_u32_e32 v16, 0x60, v14
	s_waitcnt lgkmcnt(0)
	v_mov_b64_e32 v[12:13], s[50:51]
	v_mad_i64_i32 v[14:15], s[8:9], v16, s69, 0
	v_mad_i64_i32 v[12:13], s[8:9], v16, s69, v[12:13]
	v_lshl_add_u64 v[16:17], v[140:141], 0, v[12:13]
	s_mov_b32 s8, 0
	v_mov_b32_e32 v22, 0
	v_mov_b32_e32 v22, v37
	ds_bpermute_b32 v16, v19, v22
	s_waitcnt lgkmcnt(0)
	v_add_f32_e32 v16, v22, v16
	ds_bpermute_b32 v17, v20, v16
	s_waitcnt lgkmcnt(0)
	v_add_f32_e32 v16, v16, v17
	ds_bpermute_b32 v17, v21, v16
	s_and_saveexec_b64 s[8:9], s[4:5]
	s_cbranch_execz .LBB0_513
	s_waitcnt lgkmcnt(0)
	v_add_f32_e32 v16, v16, v17
	v_div_scale_f32 v17, s[30:31], v18, v18, v16
	v_rcp_f32_e32 v19, v17
	v_div_scale_f32 v20, vcc, v16, v18, v16
	v_fma_f32 v21, -v17, v19, 1.0
	v_fmac_f32_e32 v19, v21, v19
	v_mul_f32_e32 v21, v20, v19
	v_fma_f32 v22, -v17, v21, v20
	v_fmac_f32_e32 v21, v22, v19
	v_fma_f32 v17, -v17, v21, v20
	v_div_fmas_f32 v17, v17, v19, v21
	v_div_fixup_f32 v16, v17, v18, v16
	v_add_f32_e32 v16, 0x358637bd, v16
	v_mul_f32_e32 v17, 0x4b800000, v16
	v_cmp_gt_f32_e32 vcc, s62, v16
	s_nop 1
	v_cndmask_b32_e32 v16, v16, v17, vcc
	v_rsq_f32_e32 v16, v16
	s_nop 0
	v_mul_f32_e32 v17, 0x45800000, v16
	v_cndmask_b32_e32 v16, v16, v17, vcc
	ds_write_b32 v153, v16 offset:384
